# GEMM k-loops without the 16 s_setprio toggles per iteration (64 removed)
# speedup vs baseline: 1.0100x; 1.0042x over previous
; #define PG8_STAGE(bufoff, gbase, voff) do { _Pragma("unroll") for (int _i = 0; _i < 2; ++_i) \
;         __builtin_amdgcn_global_load_lds((const unsigned*)((const char*)(gbase) + (voff)[_i]), (LAS unsigned*)(lds + (bufoff) + ldsw + _i * 8192), 16, 0, 0); } while (0)
; #define PG8_LDA(dst, b, h) do { _Pragma("unroll") for (int m = 0; m < 4; ++m) _Pragma("unroll") for (int k = 0; k < 2; ++k) dst[m][k] = *(const LAS bf16x8*)(lds + PG8_SA(b, h) + aoff + m * 2048 + k * 1024); } while (0)
; #define PG8_LDB(dst, b, h) do { _Pragma("unroll") for (int n = 0; n < 2; ++n) _Pragma("unroll") for (int k = 0; k < 2; ++k) dst[n][k] = *(const LAS bf16x8*)(lds + PG8_SB(b, h) + boff + n * 2048 + k * 1024); } while (0)
; #define PG8_MMA(ai, bj, At, Bt) do { __builtin_amdgcn_s_setprio(1); _Pragma("unroll") for (int m = 0; m < 4; ++m) _Pragma("unroll") for (int n = 0; n < 2; ++n) _Pragma("unroll") for (int k = 0; k < 2; ++k) \
;         acc[ai][bj][m][n] = __builtin_amdgcn_mfma_f32_16x16x32_bf16(Bt[n][k], At[m][k], acc[ai][bj][m][n], 0, 0, 0); __builtin_amdgcn_s_setprio(0); } while (0)
; #define PG8_WAIT_V(n) asm volatile("s_waitcnt vmcnt(" #n ")" ::: "memory")
; #define PG8_WAIT_L(n) asm volatile("s_waitcnt lgkmcnt(" #n ")" ::: "memory")
; #define PG8_BAR __builtin_amdgcn_s_barrier()
; #define PG8_SCHED __builtin_amdgcn_sched_barrier(0)
; template <class Epi, bool UPMODE>
; __device__ __forceinline__ void gemm_phase(LAS unsigned char* lds, const Gemm g, const StaticOrder& S, const Epi& E) {
;     ...
;         for (int t = 0; t < nt; t += 2) {
;             const bool last = (t == nt - 2);
;             const char* a1 = cA + (size_t)(t + 1) * kstep;
;             const char* a2 = last ? nA : cA + (size_t)(t + 2) * kstep; const char* b2 = last ? nB : cB + (size_t)(t + 2) * kstep;
;             const char* a3 = a2 + kstep; const char* b3 = b2 + kstep;
;             PG8_LDB(B0, 0, 0); PG8_LDB(B1, 0, 1); PG8_SCHED; PG8_LDA(At, 0, 0); PG8_STAGE(PG8_SA(1, 1), a1 + hstepA, voffA);
;             PG8_WAIT_V(8); PG8_WAIT_L(0); PG8_BAR; PG8_MMA(0, 0, At, B0); PG8_MMA(0, 1, At, B1); PG8_BAR; PG8_SCHED;
;             PG8_LDA(At, 0, 1); PG8_STAGE(PG8_SB(0, 0), b2, voffB); PG8_STAGE(PG8_SB(0, 1), b2 + hstepB, voffB); PG8_STAGE(PG8_SA(0, 0), a2, voffA);
;             PG8_WAIT_V(8); PG8_WAIT_L(0); PG8_BAR; PG8_MMA(1, 0, At, B0); PG8_MMA(1, 1, At, B1); PG8_BAR; PG8_SCHED;
.LBB0_162:
	s_add_u32 s28, s26, 0xfffc0080
	s_addc_u32 s29, s27, -1
	s_add_i32 s57, 0, 0x10000
	s_cmp_eq_u32 s56, 12
	s_cselect_b32 s35, s21, s29
	s_cselect_b32 s34, s52, s28
	s_cselect_b32 s29, s19, s55
	s_cselect_b32 s28, s53, s54
	s_add_i32 s60, 0, 0x14000
	v_add_u32_e32 v156, s57, v149
	v_add_u32_e32 v160, s60, v149
	ds_read_b128 v[140:143], v156
	ds_read_b128 v[144:147], v156 offset:1024
	ds_read_b128 v[152:155], v156 offset:2048
	ds_read_b128 v[156:159], v156 offset:3072
	ds_read_b128 v[176:179], v160
	ds_read_b128 v[180:183], v160 offset:1024
	ds_read_b128 v[184:187], v160 offset:2048
	ds_read_b128 v[188:191], v160 offset:3072
	v_lshl_add_u64 v[160:161], s[26:27], 0, v[136:137]
	s_add_i32 m0, s38, 0xc000
	ds_read_b128 v[192:195], v151
	ds_read_b128 v[196:199], v151 offset:1024
	ds_read_b128 v[200:203], v151 offset:2048
	ds_read_b128 v[204:207], v151 offset:3072
	ds_read_b128 v[208:211], v151 offset:4096
	ds_read_b128 v[212:215], v151 offset:5120
	ds_read_b128 v[216:219], v151 offset:6144
	ds_read_b128 v[220:223], v151 offset:7168
	global_load_lds_dwordx4 v[160:161], off
	v_lshl_add_u64 v[160:161], s[26:27], 0, v[138:139]
	s_add_i32 m0, s38, 0xe000
	s_nop 0
	global_load_lds_dwordx4 v[160:161], off
	s_waitcnt vmcnt(8)
	s_waitcnt lgkmcnt(0)
	s_barrier
	s_waitcnt lgkmcnt(0)
	v_mfma_f32_16x16x32_bf16 v[126:129], v[140:143], v[192:195], v[126:129]
	v_mfma_f32_16x16x32_bf16 v[122:125], v[152:155], v[192:195], v[122:125]
	v_mfma_f32_16x16x32_bf16 v[110:113], v[140:143], v[200:203], v[110:113]
	v_mfma_f32_16x16x32_bf16 v[106:109], v[152:155], v[200:203], v[106:109]
	v_mfma_f32_16x16x32_bf16 v[94:97], v[140:143], v[208:211], v[94:97]
	v_mfma_f32_16x16x32_bf16 v[90:93], v[152:155], v[208:211], v[90:93]
	v_mfma_f32_16x16x32_bf16 v[78:81], v[140:143], v[216:219], v[78:81]
	v_mfma_f32_16x16x32_bf16 v[74:77], v[152:155], v[216:219], v[74:77]
	v_mfma_f32_16x16x32_bf16 v[126:129], v[144:147], v[196:199], v[126:129]
	v_mfma_f32_16x16x32_bf16 v[122:125], v[156:159], v[196:199], v[122:125]
	v_mfma_f32_16x16x32_bf16 v[110:113], v[144:147], v[204:207], v[110:113]
	v_mfma_f32_16x16x32_bf16 v[106:109], v[156:159], v[204:207], v[106:109]
	v_mfma_f32_16x16x32_bf16 v[94:97], v[144:147], v[212:215], v[94:97]
	v_mfma_f32_16x16x32_bf16 v[90:93], v[156:159], v[212:215], v[90:93]
	v_mfma_f32_16x16x32_bf16 v[78:81], v[144:147], v[220:223], v[78:81]
	v_mfma_f32_16x16x32_bf16 v[74:77], v[156:159], v[220:223], v[74:77]
	v_mfma_f32_16x16x32_bf16 v[118:121], v[176:179], v[192:195], v[118:121]
	v_mfma_f32_16x16x32_bf16 v[114:117], v[184:187], v[192:195], v[114:117]
	v_mfma_f32_16x16x32_bf16 v[102:105], v[176:179], v[200:203], v[102:105]
	v_mfma_f32_16x16x32_bf16 v[98:101], v[184:187], v[200:203], v[98:101]
	v_mfma_f32_16x16x32_bf16 v[86:89], v[176:179], v[208:211], v[86:89]
	v_mfma_f32_16x16x32_bf16 v[82:85], v[184:187], v[208:211], v[82:85]
	v_mfma_f32_16x16x32_bf16 v[70:73], v[176:179], v[216:219], v[70:73]
	v_mfma_f32_16x16x32_bf16 v[66:69], v[184:187], v[216:219], v[66:69]
	v_mfma_f32_16x16x32_bf16 v[118:121], v[180:183], v[196:199], v[118:121]
	v_mfma_f32_16x16x32_bf16 v[114:117], v[188:191], v[196:199], v[114:117]
	v_mfma_f32_16x16x32_bf16 v[102:105], v[180:183], v[204:207], v[102:105]
	v_mfma_f32_16x16x32_bf16 v[98:101], v[188:191], v[204:207], v[98:101]
	v_mfma_f32_16x16x32_bf16 v[86:89], v[180:183], v[212:215], v[86:89]
	v_mfma_f32_16x16x32_bf16 v[82:85], v[188:191], v[212:215], v[82:85]
	v_mfma_f32_16x16x32_bf16 v[70:73], v[180:183], v[220:223], v[70:73]
	v_mfma_f32_16x16x32_bf16 v[66:69], v[188:191], v[220:223], v[66:69]
	s_barrier
	s_add_i32 s57, s57, s37
	v_lshl_add_u64 v[160:161], s[28:29], 0, v[162:163]
	s_mov_b32 m0, s57
	ds_read_b128 v[192:195], v151 offset:16384
	ds_read_b128 v[196:199], v151 offset:17408
	ds_read_b128 v[200:203], v151 offset:18432
	ds_read_b128 v[204:207], v151 offset:19456
	ds_read_b128 v[208:211], v151 offset:20480
	ds_read_b128 v[212:215], v151 offset:21504
	ds_read_b128 v[216:219], v151 offset:22528
	ds_read_b128 v[220:223], v151 offset:23552
	global_load_lds_dwordx4 v[160:161], off
	s_add_i32 m0, s57, 0x2000
	s_add_u32 s58, s28, 0x40000
	v_lshl_add_u64 v[224:225], s[28:29], 0, v[130:131]
	s_addc_u32 s59, s29, 0
	s_add_i32 s57, s60, s37
	global_load_lds_dwordx4 v[224:225], off
	v_lshl_add_u64 v[226:227], s[58:59], 0, v[162:163]
	s_mov_b32 m0, s57
	v_lshl_add_u64 v[228:229], s[34:35], 0, v[132:133]
	global_load_lds_dwordx4 v[226:227], off
	v_lshl_add_u64 v[226:227], s[58:59], 0, v[130:131]
	s_add_i32 m0, s57, 0x2000
	s_nop 0
	global_load_lds_dwordx4 v[226:227], off
	v_lshl_add_u64 v[226:227], s[34:35], 0, v[134:135]
	s_mov_b32 m0, s38
	s_nop 0
	global_load_lds_dwordx4 v[226:227], off
	s_mov_b32 m0, s40
	s_nop 0
	global_load_lds_dwordx4 v[228:229], off
	s_waitcnt vmcnt(8)
	s_waitcnt lgkmcnt(0)
	s_barrier
; #define PG8_STAGE(bufoff, gbase, voff) do { _Pragma("unroll") for (int _i = 0; _i < 2; ++_i) \
;         __builtin_amdgcn_global_load_lds((const unsigned*)((const char*)(gbase) + (voff)[_i]), (LAS unsigned*)(lds + (bufoff) + ldsw + _i * 8192), 16, 0, 0); } while (0)
; #define PG8_LDA(dst, b, h) do { _Pragma("unroll") for (int m = 0; m < 4; ++m) _Pragma("unroll") for (int k = 0; k < 2; ++k) dst[m][k] = *(const LAS bf16x8*)(lds + PG8_SA(b, h) + aoff + m * 2048 + k * 1024); } while (0)
; #define PG8_LDB(dst, b, h) do { _Pragma("unroll") for (int n = 0; n < 2; ++n) _Pragma("unroll") for (int k = 0; k < 2; ++k) dst[n][k] = *(const LAS bf16x8*)(lds + PG8_SB(b, h) + boff + n * 2048 + k * 1024); } while (0)
; #define PG8_MMA(ai, bj, At, Bt) do { __builtin_amdgcn_s_setprio(1); _Pragma("unroll") for (int m = 0; m < 4; ++m) _Pragma("unroll") for (int n = 0; n < 2; ++n) _Pragma("unroll") for (int k = 0; k < 2; ++k) \
;         acc[ai][bj][m][n] = __builtin_amdgcn_mfma_f32_16x16x32_bf16(Bt[n][k], At[m][k], acc[ai][bj][m][n], 0, 0, 0); __builtin_amdgcn_s_setprio(0); } while (0)
; #define PG8_WAIT_V(n) asm volatile("s_waitcnt vmcnt(" #n ")" ::: "memory")
; #define PG8_WAIT_L(n) asm volatile("s_waitcnt lgkmcnt(" #n ")" ::: "memory")
; #define PG8_BAR __builtin_amdgcn_s_barrier()
; #define PG8_SCHED __builtin_amdgcn_sched_barrier(0)
; template <class Epi, bool UPMODE>
; __device__ __forceinline__ void gemm_phase(LAS unsigned char* lds, const Gemm g, const StaticOrder& S, const Epi& E) {
;     ...
;             PG8_LDA(At, 0, 1); PG8_STAGE(PG8_SB(0, 0), b2, voffB); PG8_STAGE(PG8_SB(0, 1), b2 + hstepB, voffB); PG8_STAGE(PG8_SA(0, 0), a2, voffA);
;             PG8_WAIT_V(8); PG8_WAIT_L(0); PG8_BAR; PG8_MMA(1, 0, At, B0); PG8_MMA(1, 1, At, B1); PG8_BAR; PG8_SCHED;
;             PG8_LDB(B0, 1, 0); PG8_LDB(B1, 1, 1); PG8_SCHED; PG8_LDA(At, 1, 0); PG8_STAGE(PG8_SA(0, 1), a2 + hstepA, voffA);
;             PG8_WAIT_V(8); PG8_WAIT_L(0); PG8_BAR; PG8_MMA(0, 0, At, B0); PG8_MMA(0, 1, At, B1); PG8_BAR; PG8_SCHED;
;             PG8_LDA(At, 1, 1); PG8_STAGE(PG8_SB(1, 0), b3, voffB); PG8_STAGE(PG8_SB(1, 1), b3 + hstepB, voffB); PG8_STAGE(PG8_SA(1, 0), a3, voffA);
	s_waitcnt lgkmcnt(0)
	v_mfma_f32_16x16x32_bf16 v[62:65], v[140:143], v[192:195], v[62:65]
	v_mfma_f32_16x16x32_bf16 v[58:61], v[152:155], v[192:195], v[58:61]
	v_mfma_f32_16x16x32_bf16 v[46:49], v[140:143], v[200:203], v[46:49]
	v_mfma_f32_16x16x32_bf16 v[42:45], v[152:155], v[200:203], v[42:45]
	v_mfma_f32_16x16x32_bf16 v[30:33], v[140:143], v[208:211], v[30:33]
	v_mfma_f32_16x16x32_bf16 v[26:29], v[152:155], v[208:211], v[26:29]
	v_mfma_f32_16x16x32_bf16 v[14:17], v[140:143], v[216:219], v[14:17]
	v_mfma_f32_16x16x32_bf16 v[10:13], v[152:155], v[216:219], v[10:13]
	v_mfma_f32_16x16x32_bf16 v[62:65], v[144:147], v[196:199], v[62:65]
	v_mfma_f32_16x16x32_bf16 v[58:61], v[156:159], v[196:199], v[58:61]
	v_mfma_f32_16x16x32_bf16 v[46:49], v[144:147], v[204:207], v[46:49]
	v_mfma_f32_16x16x32_bf16 v[42:45], v[156:159], v[204:207], v[42:45]
	v_mfma_f32_16x16x32_bf16 v[30:33], v[144:147], v[212:215], v[30:33]
	v_mfma_f32_16x16x32_bf16 v[26:29], v[156:159], v[212:215], v[26:29]
	v_mfma_f32_16x16x32_bf16 v[14:17], v[144:147], v[220:223], v[14:17]
	v_mfma_f32_16x16x32_bf16 v[10:13], v[156:159], v[220:223], v[10:13]
	v_mfma_f32_16x16x32_bf16 v[54:57], v[176:179], v[192:195], v[54:57]
	v_mfma_f32_16x16x32_bf16 v[50:53], v[184:187], v[192:195], v[50:53]
	v_mfma_f32_16x16x32_bf16 v[38:41], v[176:179], v[200:203], v[38:41]
	v_mfma_f32_16x16x32_bf16 v[34:37], v[184:187], v[200:203], v[34:37]
	v_mfma_f32_16x16x32_bf16 v[22:25], v[176:179], v[208:211], v[22:25]
	v_mfma_f32_16x16x32_bf16 v[18:21], v[184:187], v[208:211], v[18:21]
	v_mfma_f32_16x16x32_bf16 v[6:9], v[176:179], v[216:219], v[6:9]
	v_mfma_f32_16x16x32_bf16 v[2:5], v[184:187], v[216:219], v[2:5]
	v_mfma_f32_16x16x32_bf16 v[54:57], v[180:183], v[196:199], v[54:57]
	v_mfma_f32_16x16x32_bf16 v[50:53], v[188:191], v[196:199], v[50:53]
	v_mfma_f32_16x16x32_bf16 v[38:41], v[180:183], v[204:207], v[38:41]
	v_mfma_f32_16x16x32_bf16 v[34:37], v[188:191], v[204:207], v[34:37]
	v_mfma_f32_16x16x32_bf16 v[22:25], v[180:183], v[212:215], v[22:25]
	v_mfma_f32_16x16x32_bf16 v[18:21], v[188:191], v[212:215], v[18:21]
	v_mfma_f32_16x16x32_bf16 v[6:9], v[180:183], v[220:223], v[6:9]
	v_mfma_f32_16x16x32_bf16 v[2:5], v[188:191], v[220:223], v[2:5]
	s_barrier
	s_add_i32 s57, 0, 0x18000
	s_add_i32 s58, 0, 0x1c000
	v_add_u32_e32 v156, s57, v149
	v_add_u32_e32 v188, s58, v149
	ds_read_b128 v[140:143], v156
	ds_read_b128 v[144:147], v156 offset:1024
	ds_read_b128 v[152:155], v156 offset:2048
	ds_read_b128 v[156:159], v156 offset:3072
	ds_read_b128 v[176:179], v188
	ds_read_b128 v[180:183], v188 offset:1024
	ds_read_b128 v[184:187], v188 offset:2048
	ds_read_b128 v[188:191], v188 offset:3072
	s_add_u32 s34, s34, 0x40000
	s_addc_u32 s35, s35, 0
	s_mov_b32 m0, s42
	v_lshl_add_u64 v[230:231], s[34:35], 0, v[134:135]
	ds_read_b128 v[192:195], v151 offset:32768
	ds_read_b128 v[196:199], v151 offset:33792
	ds_read_b128 v[200:203], v151 offset:34816
	ds_read_b128 v[204:207], v151 offset:35840
	ds_read_b128 v[208:211], v151 offset:36864
	ds_read_b128 v[212:215], v151 offset:37888
	ds_read_b128 v[216:219], v151 offset:38912
	ds_read_b128 v[220:223], v151 offset:39936
	global_load_lds_dwordx4 v[230:231], off
	v_lshl_add_u64 v[230:231], s[34:35], 0, v[132:133]
	s_mov_b32 m0, s43
	s_nop 0
	global_load_lds_dwordx4 v[230:231], off
	s_waitcnt vmcnt(8)
	s_waitcnt lgkmcnt(0)
	s_barrier
	s_waitcnt lgkmcnt(0)
	v_mfma_f32_16x16x32_bf16 v[126:129], v[140:143], v[192:195], v[126:129]
	v_mfma_f32_16x16x32_bf16 v[122:125], v[152:155], v[192:195], v[122:125]
	v_mfma_f32_16x16x32_bf16 v[110:113], v[140:143], v[200:203], v[110:113]
	v_mfma_f32_16x16x32_bf16 v[106:109], v[152:155], v[200:203], v[106:109]
	v_mfma_f32_16x16x32_bf16 v[94:97], v[140:143], v[208:211], v[94:97]
	v_mfma_f32_16x16x32_bf16 v[90:93], v[152:155], v[208:211], v[90:93]
	v_mfma_f32_16x16x32_bf16 v[78:81], v[140:143], v[216:219], v[78:81]
	v_mfma_f32_16x16x32_bf16 v[74:77], v[152:155], v[216:219], v[74:77]
	v_mfma_f32_16x16x32_bf16 v[126:129], v[144:147], v[196:199], v[126:129]
	v_mfma_f32_16x16x32_bf16 v[122:125], v[156:159], v[196:199], v[122:125]
	v_mfma_f32_16x16x32_bf16 v[110:113], v[144:147], v[204:207], v[110:113]
	v_mfma_f32_16x16x32_bf16 v[106:109], v[156:159], v[204:207], v[106:109]
	v_mfma_f32_16x16x32_bf16 v[94:97], v[144:147], v[212:215], v[94:97]
	v_mfma_f32_16x16x32_bf16 v[90:93], v[156:159], v[212:215], v[90:93]
	v_mfma_f32_16x16x32_bf16 v[78:81], v[144:147], v[220:223], v[78:81]
	v_mfma_f32_16x16x32_bf16 v[74:77], v[156:159], v[220:223], v[74:77]
	v_mfma_f32_16x16x32_bf16 v[118:121], v[176:179], v[192:195], v[118:121]
	v_mfma_f32_16x16x32_bf16 v[114:117], v[184:187], v[192:195], v[114:117]
	v_mfma_f32_16x16x32_bf16 v[102:105], v[176:179], v[200:203], v[102:105]
	v_mfma_f32_16x16x32_bf16 v[98:101], v[184:187], v[200:203], v[98:101]
	v_mfma_f32_16x16x32_bf16 v[86:89], v[176:179], v[208:211], v[86:89]
	v_mfma_f32_16x16x32_bf16 v[82:85], v[184:187], v[208:211], v[82:85]
	v_mfma_f32_16x16x32_bf16 v[70:73], v[176:179], v[216:219], v[70:73]
	v_mfma_f32_16x16x32_bf16 v[66:69], v[184:187], v[216:219], v[66:69]
	v_mfma_f32_16x16x32_bf16 v[118:121], v[180:183], v[196:199], v[118:121]
	v_mfma_f32_16x16x32_bf16 v[114:117], v[188:191], v[196:199], v[114:117]
	v_mfma_f32_16x16x32_bf16 v[102:105], v[180:183], v[204:207], v[102:105]
	v_mfma_f32_16x16x32_bf16 v[98:101], v[188:191], v[204:207], v[98:101]
	v_mfma_f32_16x16x32_bf16 v[86:89], v[180:183], v[212:215], v[86:89]
	v_mfma_f32_16x16x32_bf16 v[82:85], v[188:191], v[212:215], v[82:85]
	v_mfma_f32_16x16x32_bf16 v[70:73], v[180:183], v[220:223], v[70:73]
	v_mfma_f32_16x16x32_bf16 v[66:69], v[188:191], v[220:223], v[66:69]
	s_barrier
; #define PG8_STAGE(bufoff, gbase, voff) do { _Pragma("unroll") for (int _i = 0; _i < 2; ++_i) \
;         __builtin_amdgcn_global_load_lds((const unsigned*)((const char*)(gbase) + (voff)[_i]), (LAS unsigned*)(lds + (bufoff) + ldsw + _i * 8192), 16, 0, 0); } while (0)
; #define PG8_LDA(dst, b, h) do { _Pragma("unroll") for (int m = 0; m < 4; ++m) _Pragma("unroll") for (int k = 0; k < 2; ++k) dst[m][k] = *(const LAS bf16x8*)(lds + PG8_SA(b, h) + aoff + m * 2048 + k * 1024); } while (0)
; #define PG8_MMA(ai, bj, At, Bt) do { __builtin_amdgcn_s_setprio(1); _Pragma("unroll") for (int m = 0; m < 4; ++m) _Pragma("unroll") for (int n = 0; n < 2; ++n) _Pragma("unroll") for (int k = 0; k < 2; ++k) \
;         acc[ai][bj][m][n] = __builtin_amdgcn_mfma_f32_16x16x32_bf16(Bt[n][k], At[m][k], acc[ai][bj][m][n], 0, 0, 0); __builtin_amdgcn_s_setprio(0); } while (0)
; #define PG8_WAIT_V(n) asm volatile("s_waitcnt vmcnt(" #n ")" ::: "memory")
; #define PG8_WAIT_L(n) asm volatile("s_waitcnt lgkmcnt(" #n ")" ::: "memory")
; #define PG8_BAR __builtin_amdgcn_s_barrier()
; #define PG8_SCHED __builtin_amdgcn_sched_barrier(0)
; template <class Epi, bool UPMODE>
; __device__ __forceinline__ void gemm_phase(LAS unsigned char* lds, const Gemm g, const StaticOrder& S, const Epi& E) {
;     ...
;         for (int t = 0; t < nt; t += 2) {
;     ...
;             PG8_LDA(At, 1, 1); PG8_STAGE(PG8_SB(1, 0), b3, voffB); PG8_STAGE(PG8_SB(1, 1), b3 + hstepB, voffB); PG8_STAGE(PG8_SA(1, 0), a3, voffA);
;             PG8_WAIT_V(8); PG8_WAIT_L(0); PG8_BAR; PG8_MMA(1, 0, At, B0); PG8_MMA(1, 1, At, B1); PG8_BAR; PG8_SCHED;
;         }
	s_add_i32 s34, s57, s37
	v_lshl_add_u64 v[160:161], v[160:161], 0, s[74:75]
	s_mov_b32 m0, s34
	ds_read_b128 v[192:195], v151 offset:49152
	ds_read_b128 v[196:199], v151 offset:50176
	ds_read_b128 v[200:203], v151 offset:51200
	ds_read_b128 v[204:207], v151 offset:52224
	ds_read_b128 v[208:211], v151 offset:53248
	ds_read_b128 v[212:215], v151 offset:54272
	ds_read_b128 v[216:219], v151 offset:55296
	ds_read_b128 v[220:223], v151 offset:56320
	global_load_lds_dwordx4 v[160:161], off
	s_add_i32 m0, s34, 0x2000
	s_add_u32 s28, s28, 0x40080
	v_lshl_add_u64 v[160:161], v[224:225], 0, s[74:75]
	s_addc_u32 s29, s29, 0
	s_add_i32 s34, s58, s37
	global_load_lds_dwordx4 v[160:161], off
	v_lshl_add_u64 v[160:161], s[28:29], 0, v[162:163]
	s_mov_b32 m0, s34
	s_nop 0
	global_load_lds_dwordx4 v[160:161], off
	v_lshl_add_u64 v[160:161], s[28:29], 0, v[130:131]
	s_add_i32 m0, s34, 0x2000
	s_nop 0
	global_load_lds_dwordx4 v[160:161], off
	v_lshl_add_u64 v[160:161], v[226:227], 0, s[74:75]
	s_mov_b32 m0, s44
	s_nop 0
	global_load_lds_dwordx4 v[160:161], off
	v_lshl_add_u64 v[160:161], v[228:229], 0, s[74:75]
	s_mov_b32 m0, s46
	s_nop 0
	global_load_lds_dwordx4 v[160:161], off
	s_waitcnt vmcnt(8)
	s_waitcnt lgkmcnt(0)
	s_barrier
	s_waitcnt lgkmcnt(0)
	v_mfma_f32_16x16x32_bf16 v[62:65], v[140:143], v[192:195], v[62:65]
	v_mfma_f32_16x16x32_bf16 v[58:61], v[152:155], v[192:195], v[58:61]
	v_mfma_f32_16x16x32_bf16 v[46:49], v[140:143], v[200:203], v[46:49]
	v_mfma_f32_16x16x32_bf16 v[42:45], v[152:155], v[200:203], v[42:45]
	v_mfma_f32_16x16x32_bf16 v[30:33], v[140:143], v[208:211], v[30:33]
	v_mfma_f32_16x16x32_bf16 v[26:29], v[152:155], v[208:211], v[26:29]
	v_mfma_f32_16x16x32_bf16 v[14:17], v[140:143], v[216:219], v[14:17]
	v_mfma_f32_16x16x32_bf16 v[10:13], v[152:155], v[216:219], v[10:13]
	v_mfma_f32_16x16x32_bf16 v[62:65], v[144:147], v[196:199], v[62:65]
	v_mfma_f32_16x16x32_bf16 v[58:61], v[156:159], v[196:199], v[58:61]
	v_mfma_f32_16x16x32_bf16 v[46:49], v[144:147], v[204:207], v[46:49]
	v_mfma_f32_16x16x32_bf16 v[42:45], v[156:159], v[204:207], v[42:45]
	v_mfma_f32_16x16x32_bf16 v[30:33], v[144:147], v[212:215], v[30:33]
	v_mfma_f32_16x16x32_bf16 v[26:29], v[156:159], v[212:215], v[26:29]
	v_mfma_f32_16x16x32_bf16 v[14:17], v[144:147], v[220:223], v[14:17]
	v_mfma_f32_16x16x32_bf16 v[10:13], v[156:159], v[220:223], v[10:13]
	v_mfma_f32_16x16x32_bf16 v[54:57], v[176:179], v[192:195], v[54:57]
	v_mfma_f32_16x16x32_bf16 v[50:53], v[184:187], v[192:195], v[50:53]
	v_mfma_f32_16x16x32_bf16 v[38:41], v[176:179], v[200:203], v[38:41]
	v_mfma_f32_16x16x32_bf16 v[34:37], v[184:187], v[200:203], v[34:37]
	v_mfma_f32_16x16x32_bf16 v[22:25], v[176:179], v[208:211], v[22:25]
	v_mfma_f32_16x16x32_bf16 v[18:21], v[184:187], v[208:211], v[18:21]
	v_mfma_f32_16x16x32_bf16 v[6:9], v[176:179], v[216:219], v[6:9]
	v_mfma_f32_16x16x32_bf16 v[2:5], v[184:187], v[216:219], v[2:5]
	v_mfma_f32_16x16x32_bf16 v[54:57], v[180:183], v[196:199], v[54:57]
	v_mfma_f32_16x16x32_bf16 v[50:53], v[188:191], v[196:199], v[50:53]
	v_mfma_f32_16x16x32_bf16 v[38:41], v[180:183], v[204:207], v[38:41]
	v_mfma_f32_16x16x32_bf16 v[34:37], v[188:191], v[204:207], v[34:37]
	v_mfma_f32_16x16x32_bf16 v[22:25], v[180:183], v[212:215], v[22:25]
	v_mfma_f32_16x16x32_bf16 v[18:21], v[188:191], v[212:215], v[18:21]
	v_mfma_f32_16x16x32_bf16 v[6:9], v[180:183], v[220:223], v[6:9]
	v_mfma_f32_16x16x32_bf16 v[2:5], v[188:191], v[220:223], v[2:5]
	s_barrier
	s_add_i32 s56, s56, 2
	s_add_u32 s26, s26, 0x100
	s_addc_u32 s27, s27, 0
	s_add_u32 s54, s54, 0x100
	s_addc_u32 s55, s55, 0
	s_cmp_gt_u32 s56, 13
	s_cbranch_scc0 .LBB0_162
	s_and_b64 vcc, exec, s[16:17]
	s_cbranch_vccz .LBB0_165
	s_barrier

; #define PG8_STAGE(bufoff, gbase, voff) do { _Pragma("unroll") for (int _i = 0; _i < 2; ++_i) \
;         __builtin_amdgcn_global_load_lds((const unsigned*)((const char*)(gbase) + (voff)[_i]), (LAS unsigned*)(lds + (bufoff) + ldsw + _i * 8192), 16, 0, 0); } while (0)
; #define PG8_LDA(dst, b, h) do { _Pragma("unroll") for (int m = 0; m < 4; ++m) _Pragma("unroll") for (int k = 0; k < 2; ++k) dst[m][k] = *(const LAS bf16x8*)(lds + PG8_SA(b, h) + aoff + m * 2048 + k * 1024); } while (0)
; #define PG8_LDB(dst, b, h) do { _Pragma("unroll") for (int n = 0; n < 2; ++n) _Pragma("unroll") for (int k = 0; k < 2; ++k) dst[n][k] = *(const LAS bf16x8*)(lds + PG8_SB(b, h) + boff + n * 2048 + k * 1024); } while (0)
; #define PG8_MMA(ai, bj, At, Bt) do { __builtin_amdgcn_s_setprio(1); _Pragma("unroll") for (int m = 0; m < 4; ++m) _Pragma("unroll") for (int n = 0; n < 2; ++n) _Pragma("unroll") for (int k = 0; k < 2; ++k) \
;         acc[ai][bj][m][n] = __builtin_amdgcn_mfma_f32_16x16x32_bf16(Bt[n][k], At[m][k], acc[ai][bj][m][n], 0, 0, 0); __builtin_amdgcn_s_setprio(0); } while (0)
; #define PG8_WAIT_V(n) asm volatile("s_waitcnt vmcnt(" #n ")" ::: "memory")
; #define PG8_WAIT_L(n) asm volatile("s_waitcnt lgkmcnt(" #n ")" ::: "memory")
; #define PG8_BAR __builtin_amdgcn_s_barrier()
; #define PG8_SCHED __builtin_amdgcn_sched_barrier(0)
; template <class Epi, bool UPMODE>
; __device__ __forceinline__ void gemm_phase(LAS unsigned char* lds, const Gemm g, const StaticOrder& S, const Epi& E) {
;     ...
;         for (int t = 0; t < nt; t += 2) {
;             const bool last = (t == nt - 2);
;             const char* a1 = cA + (size_t)(t + 1) * kstep;
;             const char* a2 = last ? nA : cA + (size_t)(t + 2) * kstep; const char* b2 = last ? nB : cB + (size_t)(t + 2) * kstep;
;             const char* a3 = a2 + kstep; const char* b3 = b2 + kstep;
;             PG8_LDB(B0, 0, 0); PG8_LDB(B1, 0, 1); PG8_SCHED; PG8_LDA(At, 0, 0); PG8_STAGE(PG8_SA(1, 1), a1 + hstepA, voffA);
;             PG8_WAIT_V(8); PG8_WAIT_L(0); PG8_BAR; PG8_MMA(0, 0, At, B0); PG8_MMA(0, 1, At, B1); PG8_BAR; PG8_SCHED;
;             PG8_LDA(At, 0, 1); PG8_STAGE(PG8_SB(0, 0), b2, voffB); PG8_STAGE(PG8_SB(0, 1), b2 + hstepB, voffB); PG8_STAGE(PG8_SA(0, 0), a2, voffA);
;             PG8_WAIT_V(8); PG8_WAIT_L(0); PG8_BAR; PG8_MMA(1, 0, At, B0); PG8_MMA(1, 1, At, B1); PG8_BAR; PG8_SCHED;
.LBB0_418:
	s_add_u32 s28, s26, 0xfffc0080
	s_addc_u32 s29, s27, -1
	s_add_i32 s55, 0, 0x10000
	s_cmp_eq_u32 s54, 12
	s_cselect_b32 s35, s21, s29
	s_cselect_b32 s34, s50, s28
	v_add_u32_e32 v144, s55, v147
	s_cselect_b32 s29, s19, s53
	s_cselect_b32 s28, s51, s52
	s_add_i32 s58, 0, 0x14000
	ds_read_b128 v[140:143], v144
	ds_read_b128 v[150:153], v144 offset:1024
	ds_read_b128 v[154:157], v144 offset:2048
	ds_read_b128 v[158:161], v144 offset:3072
	v_add_u32_e32 v144, s58, v147
	ds_read_b128 v[176:179], v144
	ds_read_b128 v[180:183], v144 offset:1024
	ds_read_b128 v[184:187], v144 offset:2048
	ds_read_b128 v[188:191], v144 offset:3072
	v_lshl_add_u64 v[144:145], s[26:27], 0, v[136:137]
	s_add_i32 m0, s36, 0xc000
	ds_read_b128 v[192:195], v149
	ds_read_b128 v[196:199], v149 offset:1024
	ds_read_b128 v[200:203], v149 offset:2048
	ds_read_b128 v[204:207], v149 offset:3072
	ds_read_b128 v[208:211], v149 offset:4096
	ds_read_b128 v[212:215], v149 offset:5120
	ds_read_b128 v[216:219], v149 offset:6144
	ds_read_b128 v[220:223], v149 offset:7168
	global_load_lds_dwordx4 v[144:145], off
	v_lshl_add_u64 v[144:145], s[26:27], 0, v[138:139]
	s_add_i32 m0, s36, 0xe000
	s_nop 0
	global_load_lds_dwordx4 v[144:145], off
	s_waitcnt vmcnt(8)
	s_waitcnt lgkmcnt(0)
	s_barrier
	s_waitcnt lgkmcnt(0)
	v_mfma_f32_16x16x32_bf16 v[126:129], v[140:143], v[192:195], v[126:129]
	v_mfma_f32_16x16x32_bf16 v[122:125], v[154:157], v[192:195], v[122:125]
	v_mfma_f32_16x16x32_bf16 v[110:113], v[140:143], v[200:203], v[110:113]
	v_mfma_f32_16x16x32_bf16 v[106:109], v[154:157], v[200:203], v[106:109]
	v_mfma_f32_16x16x32_bf16 v[94:97], v[140:143], v[208:211], v[94:97]
	v_mfma_f32_16x16x32_bf16 v[90:93], v[154:157], v[208:211], v[90:93]
	v_mfma_f32_16x16x32_bf16 v[78:81], v[140:143], v[216:219], v[78:81]
	v_mfma_f32_16x16x32_bf16 v[74:77], v[154:157], v[216:219], v[74:77]
	v_mfma_f32_16x16x32_bf16 v[126:129], v[150:153], v[196:199], v[126:129]
	v_mfma_f32_16x16x32_bf16 v[122:125], v[158:161], v[196:199], v[122:125]
	v_mfma_f32_16x16x32_bf16 v[110:113], v[150:153], v[204:207], v[110:113]
	v_mfma_f32_16x16x32_bf16 v[106:109], v[158:161], v[204:207], v[106:109]
	v_mfma_f32_16x16x32_bf16 v[94:97], v[150:153], v[212:215], v[94:97]
	v_mfma_f32_16x16x32_bf16 v[90:93], v[158:161], v[212:215], v[90:93]
	v_mfma_f32_16x16x32_bf16 v[78:81], v[150:153], v[220:223], v[78:81]
	v_mfma_f32_16x16x32_bf16 v[74:77], v[158:161], v[220:223], v[74:77]
	v_mfma_f32_16x16x32_bf16 v[118:121], v[176:179], v[192:195], v[118:121]
	v_mfma_f32_16x16x32_bf16 v[114:117], v[184:187], v[192:195], v[114:117]
	v_mfma_f32_16x16x32_bf16 v[102:105], v[176:179], v[200:203], v[102:105]
	v_mfma_f32_16x16x32_bf16 v[98:101], v[184:187], v[200:203], v[98:101]
	v_mfma_f32_16x16x32_bf16 v[86:89], v[176:179], v[208:211], v[86:89]
	v_mfma_f32_16x16x32_bf16 v[82:85], v[184:187], v[208:211], v[82:85]
	v_mfma_f32_16x16x32_bf16 v[70:73], v[176:179], v[216:219], v[70:73]
	v_mfma_f32_16x16x32_bf16 v[66:69], v[184:187], v[216:219], v[66:69]
	v_mfma_f32_16x16x32_bf16 v[118:121], v[180:183], v[196:199], v[118:121]
	v_mfma_f32_16x16x32_bf16 v[114:117], v[188:191], v[196:199], v[114:117]
	v_mfma_f32_16x16x32_bf16 v[102:105], v[180:183], v[204:207], v[102:105]
	v_mfma_f32_16x16x32_bf16 v[98:101], v[188:191], v[204:207], v[98:101]
	v_mfma_f32_16x16x32_bf16 v[86:89], v[180:183], v[212:215], v[86:89]
	v_mfma_f32_16x16x32_bf16 v[82:85], v[188:191], v[212:215], v[82:85]
	v_mfma_f32_16x16x32_bf16 v[70:73], v[180:183], v[220:223], v[70:73]
	v_mfma_f32_16x16x32_bf16 v[66:69], v[188:191], v[220:223], v[66:69]
	s_barrier
	s_add_i32 s55, s55, s33
	v_lshl_add_u64 v[144:145], s[28:29], 0, v[162:163]
	s_mov_b32 m0, s55
	ds_read_b128 v[192:195], v149 offset:16384
	ds_read_b128 v[196:199], v149 offset:17408
	ds_read_b128 v[200:203], v149 offset:18432
	ds_read_b128 v[204:207], v149 offset:19456
	ds_read_b128 v[208:211], v149 offset:20480
	ds_read_b128 v[212:215], v149 offset:21504
	ds_read_b128 v[216:219], v149 offset:22528
	ds_read_b128 v[220:223], v149 offset:23552
	global_load_lds_dwordx4 v[144:145], off
	s_add_i32 m0, s55, 0x2000
	s_add_u32 s56, s28, 0x40000
	v_lshl_add_u64 v[224:225], s[28:29], 0, v[130:131]
	s_addc_u32 s57, s29, 0
	s_add_i32 s55, s58, s33
	global_load_lds_dwordx4 v[224:225], off
	v_lshl_add_u64 v[226:227], s[56:57], 0, v[162:163]
	s_mov_b32 m0, s55
	v_lshl_add_u64 v[228:229], s[34:35], 0, v[132:133]
	global_load_lds_dwordx4 v[226:227], off
	v_lshl_add_u64 v[226:227], s[56:57], 0, v[130:131]
	s_add_i32 m0, s55, 0x2000
	s_nop 0
	global_load_lds_dwordx4 v[226:227], off
	v_lshl_add_u64 v[226:227], s[34:35], 0, v[134:135]
	s_mov_b32 m0, s36
	s_nop 0
	global_load_lds_dwordx4 v[226:227], off
	s_mov_b32 m0, s37
	s_nop 0
	global_load_lds_dwordx4 v[228:229], off
	s_waitcnt vmcnt(8)
	s_waitcnt lgkmcnt(0)
	s_barrier
; #define PG8_STAGE(bufoff, gbase, voff) do { _Pragma("unroll") for (int _i = 0; _i < 2; ++_i) \
;         __builtin_amdgcn_global_load_lds((const unsigned*)((const char*)(gbase) + (voff)[_i]), (LAS unsigned*)(lds + (bufoff) + ldsw + _i * 8192), 16, 0, 0); } while (0)
; #define PG8_LDA(dst, b, h) do { _Pragma("unroll") for (int m = 0; m < 4; ++m) _Pragma("unroll") for (int k = 0; k < 2; ++k) dst[m][k] = *(const LAS bf16x8*)(lds + PG8_SA(b, h) + aoff + m * 2048 + k * 1024); } while (0)
; #define PG8_LDB(dst, b, h) do { _Pragma("unroll") for (int n = 0; n < 2; ++n) _Pragma("unroll") for (int k = 0; k < 2; ++k) dst[n][k] = *(const LAS bf16x8*)(lds + PG8_SB(b, h) + boff + n * 2048 + k * 1024); } while (0)
; #define PG8_MMA(ai, bj, At, Bt) do { __builtin_amdgcn_s_setprio(1); _Pragma("unroll") for (int m = 0; m < 4; ++m) _Pragma("unroll") for (int n = 0; n < 2; ++n) _Pragma("unroll") for (int k = 0; k < 2; ++k) \
;         acc[ai][bj][m][n] = __builtin_amdgcn_mfma_f32_16x16x32_bf16(Bt[n][k], At[m][k], acc[ai][bj][m][n], 0, 0, 0); __builtin_amdgcn_s_setprio(0); } while (0)
; #define PG8_WAIT_V(n) asm volatile("s_waitcnt vmcnt(" #n ")" ::: "memory")
; #define PG8_WAIT_L(n) asm volatile("s_waitcnt lgkmcnt(" #n ")" ::: "memory")
; #define PG8_BAR __builtin_amdgcn_s_barrier()
; #define PG8_SCHED __builtin_amdgcn_sched_barrier(0)
; template <class Epi, bool UPMODE>
; __device__ __forceinline__ void gemm_phase(LAS unsigned char* lds, const Gemm g, const StaticOrder& S, const Epi& E) {
;     ...
;             PG8_LDA(At, 0, 1); PG8_STAGE(PG8_SB(0, 0), b2, voffB); PG8_STAGE(PG8_SB(0, 1), b2 + hstepB, voffB); PG8_STAGE(PG8_SA(0, 0), a2, voffA);
;             PG8_WAIT_V(8); PG8_WAIT_L(0); PG8_BAR; PG8_MMA(1, 0, At, B0); PG8_MMA(1, 1, At, B1); PG8_BAR; PG8_SCHED;
;             PG8_LDB(B0, 1, 0); PG8_LDB(B1, 1, 1); PG8_SCHED; PG8_LDA(At, 1, 0); PG8_STAGE(PG8_SA(0, 1), a2 + hstepA, voffA);
;             PG8_WAIT_V(8); PG8_WAIT_L(0); PG8_BAR; PG8_MMA(0, 0, At, B0); PG8_MMA(0, 1, At, B1); PG8_BAR; PG8_SCHED;
;             PG8_LDA(At, 1, 1); PG8_STAGE(PG8_SB(1, 0), b3, voffB); PG8_STAGE(PG8_SB(1, 1), b3 + hstepB, voffB); PG8_STAGE(PG8_SA(1, 0), a3, voffA);
	s_waitcnt lgkmcnt(0)
	v_mfma_f32_16x16x32_bf16 v[62:65], v[140:143], v[192:195], v[62:65]
	v_mfma_f32_16x16x32_bf16 v[58:61], v[154:157], v[192:195], v[58:61]
	v_mfma_f32_16x16x32_bf16 v[46:49], v[140:143], v[200:203], v[46:49]
	v_mfma_f32_16x16x32_bf16 v[42:45], v[154:157], v[200:203], v[42:45]
	v_mfma_f32_16x16x32_bf16 v[30:33], v[140:143], v[208:211], v[30:33]
	v_mfma_f32_16x16x32_bf16 v[26:29], v[154:157], v[208:211], v[26:29]
	v_mfma_f32_16x16x32_bf16 v[14:17], v[140:143], v[216:219], v[14:17]
	v_mfma_f32_16x16x32_bf16 v[10:13], v[154:157], v[216:219], v[10:13]
	v_mfma_f32_16x16x32_bf16 v[62:65], v[150:153], v[196:199], v[62:65]
	v_mfma_f32_16x16x32_bf16 v[58:61], v[158:161], v[196:199], v[58:61]
	v_mfma_f32_16x16x32_bf16 v[46:49], v[150:153], v[204:207], v[46:49]
	v_mfma_f32_16x16x32_bf16 v[42:45], v[158:161], v[204:207], v[42:45]
	v_mfma_f32_16x16x32_bf16 v[30:33], v[150:153], v[212:215], v[30:33]
	v_mfma_f32_16x16x32_bf16 v[26:29], v[158:161], v[212:215], v[26:29]
	v_mfma_f32_16x16x32_bf16 v[14:17], v[150:153], v[220:223], v[14:17]
	v_mfma_f32_16x16x32_bf16 v[10:13], v[158:161], v[220:223], v[10:13]
	v_mfma_f32_16x16x32_bf16 v[54:57], v[176:179], v[192:195], v[54:57]
	v_mfma_f32_16x16x32_bf16 v[50:53], v[184:187], v[192:195], v[50:53]
	v_mfma_f32_16x16x32_bf16 v[38:41], v[176:179], v[200:203], v[38:41]
	v_mfma_f32_16x16x32_bf16 v[34:37], v[184:187], v[200:203], v[34:37]
	v_mfma_f32_16x16x32_bf16 v[22:25], v[176:179], v[208:211], v[22:25]
	v_mfma_f32_16x16x32_bf16 v[18:21], v[184:187], v[208:211], v[18:21]
	v_mfma_f32_16x16x32_bf16 v[6:9], v[176:179], v[216:219], v[6:9]
	v_mfma_f32_16x16x32_bf16 v[2:5], v[184:187], v[216:219], v[2:5]
	v_mfma_f32_16x16x32_bf16 v[54:57], v[180:183], v[196:199], v[54:57]
	v_mfma_f32_16x16x32_bf16 v[50:53], v[188:191], v[196:199], v[50:53]
	v_mfma_f32_16x16x32_bf16 v[38:41], v[180:183], v[204:207], v[38:41]
	v_mfma_f32_16x16x32_bf16 v[34:37], v[188:191], v[204:207], v[34:37]
	v_mfma_f32_16x16x32_bf16 v[22:25], v[180:183], v[212:215], v[22:25]
	v_mfma_f32_16x16x32_bf16 v[18:21], v[188:191], v[212:215], v[18:21]
	v_mfma_f32_16x16x32_bf16 v[6:9], v[180:183], v[220:223], v[6:9]
	v_mfma_f32_16x16x32_bf16 v[2:5], v[188:191], v[220:223], v[2:5]
	s_barrier
	s_add_i32 s55, 0, 0x18000
	s_add_i32 s56, 0, 0x1c000
	v_add_u32_e32 v158, s55, v147
	v_add_u32_e32 v188, s56, v147
	ds_read_b128 v[140:143], v158
	ds_read_b128 v[150:153], v158 offset:1024
	ds_read_b128 v[154:157], v158 offset:2048
	ds_read_b128 v[158:161], v158 offset:3072
	ds_read_b128 v[176:179], v188
	ds_read_b128 v[180:183], v188 offset:1024
	ds_read_b128 v[184:187], v188 offset:2048
	ds_read_b128 v[188:191], v188 offset:3072
	s_add_u32 s34, s34, 0x40000
	s_addc_u32 s35, s35, 0
	s_mov_b32 m0, s38
	v_lshl_add_u64 v[230:231], s[34:35], 0, v[134:135]
	ds_read_b128 v[192:195], v149 offset:32768
	ds_read_b128 v[196:199], v149 offset:33792
	ds_read_b128 v[200:203], v149 offset:34816
	ds_read_b128 v[204:207], v149 offset:35840
	ds_read_b128 v[208:211], v149 offset:36864
	ds_read_b128 v[212:215], v149 offset:37888
	ds_read_b128 v[216:219], v149 offset:38912
	ds_read_b128 v[220:223], v149 offset:39936
	global_load_lds_dwordx4 v[230:231], off
	v_lshl_add_u64 v[230:231], s[34:35], 0, v[132:133]
	s_mov_b32 m0, s40
	s_nop 0
	global_load_lds_dwordx4 v[230:231], off
	s_waitcnt vmcnt(8)
	s_waitcnt lgkmcnt(0)
	s_barrier
	s_waitcnt lgkmcnt(0)
	v_mfma_f32_16x16x32_bf16 v[126:129], v[140:143], v[192:195], v[126:129]
	v_mfma_f32_16x16x32_bf16 v[122:125], v[154:157], v[192:195], v[122:125]
	v_mfma_f32_16x16x32_bf16 v[110:113], v[140:143], v[200:203], v[110:113]
	v_mfma_f32_16x16x32_bf16 v[106:109], v[154:157], v[200:203], v[106:109]
	v_mfma_f32_16x16x32_bf16 v[94:97], v[140:143], v[208:211], v[94:97]
	v_mfma_f32_16x16x32_bf16 v[90:93], v[154:157], v[208:211], v[90:93]
	v_mfma_f32_16x16x32_bf16 v[78:81], v[140:143], v[216:219], v[78:81]
	v_mfma_f32_16x16x32_bf16 v[74:77], v[154:157], v[216:219], v[74:77]
	v_mfma_f32_16x16x32_bf16 v[126:129], v[150:153], v[196:199], v[126:129]
	v_mfma_f32_16x16x32_bf16 v[122:125], v[158:161], v[196:199], v[122:125]
	v_mfma_f32_16x16x32_bf16 v[110:113], v[150:153], v[204:207], v[110:113]
	v_mfma_f32_16x16x32_bf16 v[106:109], v[158:161], v[204:207], v[106:109]
	v_mfma_f32_16x16x32_bf16 v[94:97], v[150:153], v[212:215], v[94:97]
	v_mfma_f32_16x16x32_bf16 v[90:93], v[158:161], v[212:215], v[90:93]
	v_mfma_f32_16x16x32_bf16 v[78:81], v[150:153], v[220:223], v[78:81]
	v_mfma_f32_16x16x32_bf16 v[74:77], v[158:161], v[220:223], v[74:77]
	v_mfma_f32_16x16x32_bf16 v[118:121], v[176:179], v[192:195], v[118:121]
	v_mfma_f32_16x16x32_bf16 v[114:117], v[184:187], v[192:195], v[114:117]
	v_mfma_f32_16x16x32_bf16 v[102:105], v[176:179], v[200:203], v[102:105]
	v_mfma_f32_16x16x32_bf16 v[98:101], v[184:187], v[200:203], v[98:101]
	v_mfma_f32_16x16x32_bf16 v[86:89], v[176:179], v[208:211], v[86:89]
	v_mfma_f32_16x16x32_bf16 v[82:85], v[184:187], v[208:211], v[82:85]
	v_mfma_f32_16x16x32_bf16 v[70:73], v[176:179], v[216:219], v[70:73]
	v_mfma_f32_16x16x32_bf16 v[66:69], v[184:187], v[216:219], v[66:69]
	v_mfma_f32_16x16x32_bf16 v[118:121], v[180:183], v[196:199], v[118:121]
	v_mfma_f32_16x16x32_bf16 v[114:117], v[188:191], v[196:199], v[114:117]
	v_mfma_f32_16x16x32_bf16 v[102:105], v[180:183], v[204:207], v[102:105]
	v_mfma_f32_16x16x32_bf16 v[98:101], v[188:191], v[204:207], v[98:101]
	v_mfma_f32_16x16x32_bf16 v[86:89], v[180:183], v[212:215], v[86:89]
	v_mfma_f32_16x16x32_bf16 v[82:85], v[188:191], v[212:215], v[82:85]
	v_mfma_f32_16x16x32_bf16 v[70:73], v[180:183], v[220:223], v[70:73]
	v_mfma_f32_16x16x32_bf16 v[66:69], v[188:191], v[220:223], v[66:69]
	s_barrier
; #define PG8_STAGE(bufoff, gbase, voff) do { _Pragma("unroll") for (int _i = 0; _i < 2; ++_i) \
;         __builtin_amdgcn_global_load_lds((const unsigned*)((const char*)(gbase) + (voff)[_i]), (LAS unsigned*)(lds + (bufoff) + ldsw + _i * 8192), 16, 0, 0); } while (0)
; #define PG8_LDA(dst, b, h) do { _Pragma("unroll") for (int m = 0; m < 4; ++m) _Pragma("unroll") for (int k = 0; k < 2; ++k) dst[m][k] = *(const LAS bf16x8*)(lds + PG8_SA(b, h) + aoff + m * 2048 + k * 1024); } while (0)
; #define PG8_MMA(ai, bj, At, Bt) do { __builtin_amdgcn_s_setprio(1); _Pragma("unroll") for (int m = 0; m < 4; ++m) _Pragma("unroll") for (int n = 0; n < 2; ++n) _Pragma("unroll") for (int k = 0; k < 2; ++k) \
;         acc[ai][bj][m][n] = __builtin_amdgcn_mfma_f32_16x16x32_bf16(Bt[n][k], At[m][k], acc[ai][bj][m][n], 0, 0, 0); __builtin_amdgcn_s_setprio(0); } while (0)
; #define PG8_WAIT_V(n) asm volatile("s_waitcnt vmcnt(" #n ")" ::: "memory")
; #define PG8_WAIT_L(n) asm volatile("s_waitcnt lgkmcnt(" #n ")" ::: "memory")
; #define PG8_BAR __builtin_amdgcn_s_barrier()
; #define PG8_SCHED __builtin_amdgcn_sched_barrier(0)
; template <class Epi, bool UPMODE>
; __device__ __forceinline__ void gemm_phase(LAS unsigned char* lds, const Gemm g, const StaticOrder& S, const Epi& E) {
;     ...
;         for (int t = 0; t < nt; t += 2) {
;     ...
;             PG8_LDA(At, 1, 1); PG8_STAGE(PG8_SB(1, 0), b3, voffB); PG8_STAGE(PG8_SB(1, 1), b3 + hstepB, voffB); PG8_STAGE(PG8_SA(1, 0), a3, voffA);
;             PG8_WAIT_V(8); PG8_WAIT_L(0); PG8_BAR; PG8_MMA(1, 0, At, B0); PG8_MMA(1, 1, At, B1); PG8_BAR; PG8_SCHED;
;         }
	s_add_i32 s34, s55, s33
	v_lshl_add_u64 v[144:145], v[144:145], 0, s[74:75]
	s_mov_b32 m0, s34
	ds_read_b128 v[192:195], v149 offset:49152
	ds_read_b128 v[196:199], v149 offset:50176
	ds_read_b128 v[200:203], v149 offset:51200
	ds_read_b128 v[204:207], v149 offset:52224
	ds_read_b128 v[208:211], v149 offset:53248
	ds_read_b128 v[212:215], v149 offset:54272
	ds_read_b128 v[216:219], v149 offset:55296
	ds_read_b128 v[220:223], v149 offset:56320
	global_load_lds_dwordx4 v[144:145], off
	s_add_i32 m0, s34, 0x2000
	s_add_u32 s28, s28, 0x40080
	v_lshl_add_u64 v[144:145], v[224:225], 0, s[74:75]
	s_addc_u32 s29, s29, 0
	s_add_i32 s34, s56, s33
	global_load_lds_dwordx4 v[144:145], off
	v_lshl_add_u64 v[144:145], s[28:29], 0, v[162:163]
	s_mov_b32 m0, s34
	s_nop 0
	global_load_lds_dwordx4 v[144:145], off
	v_lshl_add_u64 v[144:145], s[28:29], 0, v[130:131]
	s_add_i32 m0, s34, 0x2000
	s_nop 0
	global_load_lds_dwordx4 v[144:145], off
	v_lshl_add_u64 v[144:145], v[226:227], 0, s[74:75]
	s_mov_b32 m0, s42
	s_nop 0
	global_load_lds_dwordx4 v[144:145], off
	v_lshl_add_u64 v[144:145], v[228:229], 0, s[74:75]
	s_mov_b32 m0, s43
	s_nop 0
	global_load_lds_dwordx4 v[144:145], off
	s_waitcnt vmcnt(8)
	s_waitcnt lgkmcnt(0)
	s_barrier
	s_waitcnt lgkmcnt(0)
	v_mfma_f32_16x16x32_bf16 v[62:65], v[140:143], v[192:195], v[62:65]
	v_mfma_f32_16x16x32_bf16 v[58:61], v[154:157], v[192:195], v[58:61]
	v_mfma_f32_16x16x32_bf16 v[46:49], v[140:143], v[200:203], v[46:49]
	v_mfma_f32_16x16x32_bf16 v[42:45], v[154:157], v[200:203], v[42:45]
	v_mfma_f32_16x16x32_bf16 v[30:33], v[140:143], v[208:211], v[30:33]
	v_mfma_f32_16x16x32_bf16 v[26:29], v[154:157], v[208:211], v[26:29]
	v_mfma_f32_16x16x32_bf16 v[14:17], v[140:143], v[216:219], v[14:17]
	v_mfma_f32_16x16x32_bf16 v[10:13], v[154:157], v[216:219], v[10:13]
	v_mfma_f32_16x16x32_bf16 v[62:65], v[150:153], v[196:199], v[62:65]
	v_mfma_f32_16x16x32_bf16 v[58:61], v[158:161], v[196:199], v[58:61]
	v_mfma_f32_16x16x32_bf16 v[46:49], v[150:153], v[204:207], v[46:49]
	v_mfma_f32_16x16x32_bf16 v[42:45], v[158:161], v[204:207], v[42:45]
	v_mfma_f32_16x16x32_bf16 v[30:33], v[150:153], v[212:215], v[30:33]
	v_mfma_f32_16x16x32_bf16 v[26:29], v[158:161], v[212:215], v[26:29]
	v_mfma_f32_16x16x32_bf16 v[14:17], v[150:153], v[220:223], v[14:17]
	v_mfma_f32_16x16x32_bf16 v[10:13], v[158:161], v[220:223], v[10:13]
	v_mfma_f32_16x16x32_bf16 v[54:57], v[176:179], v[192:195], v[54:57]
	v_mfma_f32_16x16x32_bf16 v[50:53], v[184:187], v[192:195], v[50:53]
	v_mfma_f32_16x16x32_bf16 v[38:41], v[176:179], v[200:203], v[38:41]
	v_mfma_f32_16x16x32_bf16 v[34:37], v[184:187], v[200:203], v[34:37]
	v_mfma_f32_16x16x32_bf16 v[22:25], v[176:179], v[208:211], v[22:25]
	v_mfma_f32_16x16x32_bf16 v[18:21], v[184:187], v[208:211], v[18:21]
	v_mfma_f32_16x16x32_bf16 v[6:9], v[176:179], v[216:219], v[6:9]
	v_mfma_f32_16x16x32_bf16 v[2:5], v[184:187], v[216:219], v[2:5]
	v_mfma_f32_16x16x32_bf16 v[54:57], v[180:183], v[196:199], v[54:57]
	v_mfma_f32_16x16x32_bf16 v[50:53], v[188:191], v[196:199], v[50:53]
	v_mfma_f32_16x16x32_bf16 v[38:41], v[180:183], v[204:207], v[38:41]
	v_mfma_f32_16x16x32_bf16 v[34:37], v[188:191], v[204:207], v[34:37]
	v_mfma_f32_16x16x32_bf16 v[22:25], v[180:183], v[212:215], v[22:25]
	v_mfma_f32_16x16x32_bf16 v[18:21], v[188:191], v[212:215], v[18:21]
	v_mfma_f32_16x16x32_bf16 v[6:9], v[180:183], v[220:223], v[6:9]
	v_mfma_f32_16x16x32_bf16 v[2:5], v[188:191], v[220:223], v[2:5]
	s_barrier
	s_add_i32 s54, s54, 2
	s_add_u32 s26, s26, 0x100
	s_addc_u32 s27, s27, 0
	s_add_u32 s52, s52, 0x100
	s_addc_u32 s53, s53, 0
	s_cmp_gt_u32 s54, 13
	s_cbranch_scc0 .LBB0_418
	s_and_b64 vcc, exec, s[16:17]
	s_cbranch_vccz .LBB0_421
	s_barrier

; #define PG8_STAGE(bufoff, gbase, voff) do { _Pragma("unroll") for (int _i = 0; _i < 2; ++_i) \
;         __builtin_amdgcn_global_load_lds((const unsigned*)((const char*)(gbase) + (voff)[_i]), (LAS unsigned*)(lds + (bufoff) + ldsw + _i * 8192), 16, 0, 0); } while (0)
; #define PG8_LDA(dst, b, h) do { _Pragma("unroll") for (int m = 0; m < 4; ++m) _Pragma("unroll") for (int k = 0; k < 2; ++k) dst[m][k] = *(const LAS bf16x8*)(lds + PG8_SA(b, h) + aoff + m * 2048 + k * 1024); } while (0)
; #define PG8_LDB(dst, b, h) do { _Pragma("unroll") for (int n = 0; n < 2; ++n) _Pragma("unroll") for (int k = 0; k < 2; ++k) dst[n][k] = *(const LAS bf16x8*)(lds + PG8_SB(b, h) + boff + n * 2048 + k * 1024); } while (0)
; #define PG8_MMA(ai, bj, At, Bt) do { __builtin_amdgcn_s_setprio(1); _Pragma("unroll") for (int m = 0; m < 4; ++m) _Pragma("unroll") for (int n = 0; n < 2; ++n) _Pragma("unroll") for (int k = 0; k < 2; ++k) \
;         acc[ai][bj][m][n] = __builtin_amdgcn_mfma_f32_16x16x32_bf16(Bt[n][k], At[m][k], acc[ai][bj][m][n], 0, 0, 0); __builtin_amdgcn_s_setprio(0); } while (0)
; #define PG8_WAIT_V(n) asm volatile("s_waitcnt vmcnt(" #n ")" ::: "memory")
; #define PG8_WAIT_L(n) asm volatile("s_waitcnt lgkmcnt(" #n ")" ::: "memory")
; #define PG8_BAR __builtin_amdgcn_s_barrier()
; #define PG8_SCHED __builtin_amdgcn_sched_barrier(0)
; template <class Epi, bool UPMODE>
; __device__ __forceinline__ void gemm_phase(LAS unsigned char* lds, const Gemm g, const StaticOrder& S, const Epi& E) {
;     ...
;         for (int t = 0; t < nt; t += 2) {
;             const bool last = (t == nt - 2);
;             const char* a1 = cA + (size_t)(t + 1) * kstep;
;             const char* a2 = last ? nA : cA + (size_t)(t + 2) * kstep; const char* b2 = last ? nB : cB + (size_t)(t + 2) * kstep;
;             const char* a3 = a2 + kstep; const char* b3 = b2 + kstep;
;             PG8_LDB(B0, 0, 0); PG8_LDB(B1, 0, 1); PG8_SCHED; PG8_LDA(At, 0, 0); PG8_STAGE(PG8_SA(1, 1), a1 + hstepA, voffA);
;             PG8_WAIT_V(8); PG8_WAIT_L(0); PG8_BAR; PG8_MMA(0, 0, At, B0); PG8_MMA(0, 1, At, B1); PG8_BAR; PG8_SCHED;
;             PG8_LDA(At, 0, 1); PG8_STAGE(PG8_SB(0, 0), b2, voffB); PG8_STAGE(PG8_SB(0, 1), b2 + hstepB, voffB); PG8_STAGE(PG8_SA(0, 0), a2, voffA);
;             PG8_WAIT_V(8); PG8_WAIT_L(0); PG8_BAR; PG8_MMA(1, 0, At, B0); PG8_MMA(1, 1, At, B1); PG8_BAR; PG8_SCHED;
.LBB0_595:
	s_add_u32 s10, s14, 0x100
	s_addc_u32 s11, s15, 0
	s_add_i32 s25, 0, 0x10000
	s_cmp_eq_u32 s24, 12
	s_cselect_b32 s19, s73, s11
	s_cselect_b32 s18, s72, s10
	s_cselect_b32 s17, s13, s23
	s_cselect_b32 s16, s20, s21
	s_add_i32 s28, 0, 0x14000
	v_add_u32_e32 v118, s25, v251
	v_add_u32_e32 v138, s28, v251
	ds_read_b128 v[106:109], v118
	ds_read_b128 v[110:113], v118 offset:1024
	ds_read_b128 v[114:117], v118 offset:2048
	ds_read_b128 v[118:121], v118 offset:3072
	ds_read_b128 v[122:125], v138
	ds_read_b128 v[126:129], v138 offset:1024
	ds_read_b128 v[130:133], v138 offset:2048
	ds_read_b128 v[138:141], v138 offset:3072
	v_lshl_add_u64 v[218:219], s[14:15], 0, v[182:183]
	s_add_i32 m0, s44, 0xc000
	ds_read_b128 v[186:189], v254
	ds_read_b128 v[190:193], v254 offset:1024
	ds_read_b128 v[194:197], v254 offset:2048
	ds_read_b128 v[198:201], v254 offset:3072
	ds_read_b128 v[202:205], v254 offset:4096
	ds_read_b128 v[206:209], v254 offset:5120
	ds_read_b128 v[210:213], v254 offset:6144
	ds_read_b128 v[214:217], v254 offset:7168
	global_load_lds_dwordx4 v[218:219], off
	v_lshl_add_u64 v[218:219], s[14:15], 0, v[184:185]
	s_add_i32 m0, s44, 0xe000
	s_nop 0
	global_load_lds_dwordx4 v[218:219], off
	s_waitcnt vmcnt(8)
	s_waitcnt lgkmcnt(0)
	s_barrier
	s_waitcnt lgkmcnt(0)
	v_mfma_f32_16x16x32_bf16 v[158:161], v[106:109], v[186:189], v[158:161]
	v_mfma_f32_16x16x32_bf16 v[62:65], v[114:117], v[186:189], v[62:65]
	v_mfma_f32_16x16x32_bf16 v[154:157], v[106:109], v[194:197], v[154:157]
	v_mfma_f32_16x16x32_bf16 v[58:61], v[114:117], v[194:197], v[58:61]
	v_mfma_f32_16x16x32_bf16 v[102:105], v[106:109], v[202:205], v[102:105]
	v_mfma_f32_16x16x32_bf16 v[38:41], v[114:117], v[202:205], v[38:41]
	v_mfma_f32_16x16x32_bf16 v[94:97], v[106:109], v[210:213], v[94:97]
	v_mfma_f32_16x16x32_bf16 v[30:33], v[114:117], v[210:213], v[30:33]
	v_mfma_f32_16x16x32_bf16 v[158:161], v[110:113], v[190:193], v[158:161]
	v_mfma_f32_16x16x32_bf16 v[62:65], v[118:121], v[190:193], v[62:65]
	v_mfma_f32_16x16x32_bf16 v[154:157], v[110:113], v[198:201], v[154:157]
	v_mfma_f32_16x16x32_bf16 v[58:61], v[118:121], v[198:201], v[58:61]
	v_mfma_f32_16x16x32_bf16 v[102:105], v[110:113], v[206:209], v[102:105]
	v_mfma_f32_16x16x32_bf16 v[38:41], v[118:121], v[206:209], v[38:41]
	v_mfma_f32_16x16x32_bf16 v[94:97], v[110:113], v[214:217], v[94:97]
	v_mfma_f32_16x16x32_bf16 v[30:33], v[118:121], v[214:217], v[30:33]
	v_mfma_f32_16x16x32_bf16 v[150:153], v[122:125], v[186:189], v[150:153]
	v_mfma_f32_16x16x32_bf16 v[54:57], v[130:133], v[186:189], v[54:57]
	v_mfma_f32_16x16x32_bf16 v[146:149], v[122:125], v[194:197], v[146:149]
	v_mfma_f32_16x16x32_bf16 v[50:53], v[130:133], v[194:197], v[50:53]
	v_mfma_f32_16x16x32_bf16 v[98:101], v[122:125], v[202:205], v[98:101]
	v_mfma_f32_16x16x32_bf16 v[34:37], v[130:133], v[202:205], v[34:37]
	v_mfma_f32_16x16x32_bf16 v[90:93], v[122:125], v[210:213], v[90:93]
	v_mfma_f32_16x16x32_bf16 v[26:29], v[130:133], v[210:213], v[26:29]
	v_mfma_f32_16x16x32_bf16 v[150:153], v[126:129], v[190:193], v[150:153]
	v_mfma_f32_16x16x32_bf16 v[54:57], v[138:141], v[190:193], v[54:57]
	v_mfma_f32_16x16x32_bf16 v[146:149], v[126:129], v[198:201], v[146:149]
	v_mfma_f32_16x16x32_bf16 v[50:53], v[138:141], v[198:201], v[50:53]
	v_mfma_f32_16x16x32_bf16 v[98:101], v[126:129], v[206:209], v[98:101]
	v_mfma_f32_16x16x32_bf16 v[34:37], v[138:141], v[206:209], v[34:37]
	v_mfma_f32_16x16x32_bf16 v[90:93], v[126:129], v[214:217], v[90:93]
	v_mfma_f32_16x16x32_bf16 v[26:29], v[138:141], v[214:217], v[26:29]
	s_barrier
	s_add_i32 s14, s25, s51
	v_lshl_add_u64 v[222:223], s[16:17], 0, v[162:163]
	s_mov_b32 m0, s14
	ds_read_b128 v[186:189], v254 offset:16384
	ds_read_b128 v[190:193], v254 offset:17408
	ds_read_b128 v[194:197], v254 offset:18432
	ds_read_b128 v[198:201], v254 offset:19456
	ds_read_b128 v[202:205], v254 offset:20480
	ds_read_b128 v[206:209], v254 offset:21504
	ds_read_b128 v[210:213], v254 offset:22528
	ds_read_b128 v[214:217], v254 offset:23552
	global_load_lds_dwordx4 v[222:223], off
	s_add_i32 m0, s14, 0x2000
	s_add_u32 s14, s16, 0x40000
	v_lshl_add_u64 v[224:225], s[16:17], 0, v[180:181]
	s_addc_u32 s15, s17, 0
	s_add_i32 s25, s28, s51
	global_load_lds_dwordx4 v[224:225], off
	v_lshl_add_u64 v[218:219], s[14:15], 0, v[162:163]
	s_mov_b32 m0, s25
	v_lshl_add_u64 v[226:227], s[18:19], 0, v[176:177]
	global_load_lds_dwordx4 v[218:219], off
	v_lshl_add_u64 v[218:219], s[14:15], 0, v[180:181]
	s_add_i32 m0, s25, 0x2000
	v_lshl_add_u64 v[228:229], s[18:19], 0, v[178:179]
	global_load_lds_dwordx4 v[218:219], off
	s_mov_b32 m0, s44
	s_nop 0
	global_load_lds_dwordx4 v[226:227], off
	s_mov_b32 m0, s30
	s_nop 0
	global_load_lds_dwordx4 v[228:229], off
	s_waitcnt vmcnt(8)
	s_waitcnt lgkmcnt(0)
	s_barrier
; #define PG8_STAGE(bufoff, gbase, voff) do { _Pragma("unroll") for (int _i = 0; _i < 2; ++_i) \
;         __builtin_amdgcn_global_load_lds((const unsigned*)((const char*)(gbase) + (voff)[_i]), (LAS unsigned*)(lds + (bufoff) + ldsw + _i * 8192), 16, 0, 0); } while (0)
; #define PG8_LDA(dst, b, h) do { _Pragma("unroll") for (int m = 0; m < 4; ++m) _Pragma("unroll") for (int k = 0; k < 2; ++k) dst[m][k] = *(const LAS bf16x8*)(lds + PG8_SA(b, h) + aoff + m * 2048 + k * 1024); } while (0)
; #define PG8_LDB(dst, b, h) do { _Pragma("unroll") for (int n = 0; n < 2; ++n) _Pragma("unroll") for (int k = 0; k < 2; ++k) dst[n][k] = *(const LAS bf16x8*)(lds + PG8_SB(b, h) + boff + n * 2048 + k * 1024); } while (0)
; #define PG8_MMA(ai, bj, At, Bt) do { __builtin_amdgcn_s_setprio(1); _Pragma("unroll") for (int m = 0; m < 4; ++m) _Pragma("unroll") for (int n = 0; n < 2; ++n) _Pragma("unroll") for (int k = 0; k < 2; ++k) \
;         acc[ai][bj][m][n] = __builtin_amdgcn_mfma_f32_16x16x32_bf16(Bt[n][k], At[m][k], acc[ai][bj][m][n], 0, 0, 0); __builtin_amdgcn_s_setprio(0); } while (0)
; #define PG8_WAIT_V(n) asm volatile("s_waitcnt vmcnt(" #n ")" ::: "memory")
; #define PG8_WAIT_L(n) asm volatile("s_waitcnt lgkmcnt(" #n ")" ::: "memory")
; #define PG8_BAR __builtin_amdgcn_s_barrier()
; #define PG8_SCHED __builtin_amdgcn_sched_barrier(0)
; template <class Epi, bool UPMODE>
; __device__ __forceinline__ void gemm_phase(LAS unsigned char* lds, const Gemm g, const StaticOrder& S, const Epi& E) {
;     ...
;             PG8_LDA(At, 0, 1); PG8_STAGE(PG8_SB(0, 0), b2, voffB); PG8_STAGE(PG8_SB(0, 1), b2 + hstepB, voffB); PG8_STAGE(PG8_SA(0, 0), a2, voffA);
;             PG8_WAIT_V(8); PG8_WAIT_L(0); PG8_BAR; PG8_MMA(1, 0, At, B0); PG8_MMA(1, 1, At, B1); PG8_BAR; PG8_SCHED;
;             PG8_LDB(B0, 1, 0); PG8_LDB(B1, 1, 1); PG8_SCHED; PG8_LDA(At, 1, 0); PG8_STAGE(PG8_SA(0, 1), a2 + hstepA, voffA);
;             PG8_WAIT_V(8); PG8_WAIT_L(0); PG8_BAR; PG8_MMA(0, 0, At, B0); PG8_MMA(0, 1, At, B1); PG8_BAR; PG8_SCHED;
;             PG8_LDA(At, 1, 1); PG8_STAGE(PG8_SB(1, 0), b3, voffB); PG8_STAGE(PG8_SB(1, 1), b3 + hstepB, voffB); PG8_STAGE(PG8_SA(1, 0), a3, voffA);
	s_waitcnt lgkmcnt(0)
	v_mfma_f32_16x16x32_bf16 v[86:89], v[106:109], v[186:189], v[86:89]
	v_mfma_f32_16x16x32_bf16 v[22:25], v[114:117], v[186:189], v[22:25]
	v_mfma_f32_16x16x32_bf16 v[78:81], v[106:109], v[194:197], v[78:81]
	v_mfma_f32_16x16x32_bf16 v[14:17], v[114:117], v[194:197], v[14:17]
	v_mfma_f32_16x16x32_bf16 v[70:73], v[106:109], v[202:205], v[70:73]
	v_mfma_f32_16x16x32_bf16 v[6:9], v[114:117], v[202:205], v[6:9]
	v_mfma_f32_16x16x32_bf16 v[46:49], v[114:117], v[210:213], v[46:49]
	v_mfma_f32_16x16x32_bf16 v[86:89], v[110:113], v[190:193], v[86:89]
	v_mfma_f32_16x16x32_bf16 v[22:25], v[118:121], v[190:193], v[22:25]
	v_mfma_f32_16x16x32_bf16 v[78:81], v[110:113], v[198:201], v[78:81]
	v_mfma_f32_16x16x32_bf16 v[14:17], v[118:121], v[198:201], v[14:17]
	v_mfma_f32_16x16x32_bf16 v[70:73], v[110:113], v[206:209], v[70:73]
	v_mfma_f32_16x16x32_bf16 v[6:9], v[118:121], v[206:209], v[6:9]
	v_mfma_f32_16x16x32_bf16 v[106:109], v[106:109], v[210:213], v[142:145]
	v_mfma_f32_16x16x32_bf16 v[46:49], v[118:121], v[214:217], v[46:49]
	v_mfma_f32_16x16x32_bf16 v[106:109], v[110:113], v[214:217], v[106:109]
	v_mfma_f32_16x16x32_bf16 v[82:85], v[122:125], v[186:189], v[82:85]
	v_mfma_f32_16x16x32_bf16 v[18:21], v[130:133], v[186:189], v[18:21]
	v_mfma_f32_16x16x32_bf16 v[74:77], v[122:125], v[194:197], v[74:77]
	v_mfma_f32_16x16x32_bf16 v[10:13], v[130:133], v[194:197], v[10:13]
	v_mfma_f32_16x16x32_bf16 v[66:69], v[122:125], v[202:205], v[66:69]
	v_mfma_f32_16x16x32_bf16 v[2:5], v[130:133], v[202:205], v[2:5]
	v_mfma_f32_16x16x32_bf16 v[42:45], v[130:133], v[210:213], v[42:45]
	v_mfma_f32_16x16x32_bf16 v[82:85], v[126:129], v[190:193], v[82:85]
	v_mfma_f32_16x16x32_bf16 v[18:21], v[138:141], v[190:193], v[18:21]
	v_mfma_f32_16x16x32_bf16 v[74:77], v[126:129], v[198:201], v[74:77]
	v_mfma_f32_16x16x32_bf16 v[10:13], v[138:141], v[198:201], v[10:13]
	v_mfma_f32_16x16x32_bf16 v[66:69], v[126:129], v[206:209], v[66:69]
	v_mfma_f32_16x16x32_bf16 v[2:5], v[138:141], v[206:209], v[2:5]
	v_mfma_f32_16x16x32_bf16 v[110:113], v[122:125], v[210:213], v[134:137]
	v_mfma_f32_16x16x32_bf16 v[42:45], v[138:141], v[214:217], v[42:45]
	v_mfma_f32_16x16x32_bf16 v[110:113], v[126:129], v[214:217], v[110:113]
	s_barrier
	s_add_i32 s25, 0, 0x18000
	s_add_i32 s28, 0, 0x1c000
	v_add_u32_e32 v126, s25, v251
	v_add_u32_e32 v142, s28, v251
	ds_read_b128 v[114:117], v126
	ds_read_b128 v[118:121], v126 offset:1024
	ds_read_b128 v[122:125], v126 offset:2048
	ds_read_b128 v[126:129], v126 offset:3072
	ds_read_b128 v[130:133], v142
	ds_read_b128 v[134:137], v142 offset:1024
	ds_read_b128 v[138:141], v142 offset:2048
	ds_read_b128 v[186:189], v142 offset:3072
	s_add_u32 s14, s18, 0x2000
	s_addc_u32 s15, s19, 0
	s_mov_b32 m0, s31
	v_lshl_add_u64 v[218:219], s[14:15], 0, v[176:177]
	ds_read_b128 v[142:145], v254 offset:32768
	ds_read_b128 v[190:193], v254 offset:33792
	ds_read_b128 v[194:197], v254 offset:34816
	ds_read_b128 v[198:201], v254 offset:35840
	ds_read_b128 v[202:205], v254 offset:36864
	ds_read_b128 v[206:209], v254 offset:37888
	ds_read_b128 v[210:213], v254 offset:38912
	ds_read_b128 v[214:217], v254 offset:39936
	global_load_lds_dwordx4 v[218:219], off
	v_lshl_add_u64 v[218:219], s[14:15], 0, v[178:179]
	s_mov_b32 m0, s46
	s_nop 0
	global_load_lds_dwordx4 v[218:219], off
	s_waitcnt vmcnt(8)
	s_waitcnt lgkmcnt(0)
	s_barrier
	s_waitcnt lgkmcnt(0)
	v_mfma_f32_16x16x32_bf16 v[158:161], v[114:117], v[142:145], v[158:161]
	v_mfma_f32_16x16x32_bf16 v[62:65], v[122:125], v[142:145], v[62:65]
	v_mfma_f32_16x16x32_bf16 v[154:157], v[114:117], v[194:197], v[154:157]
	v_mfma_f32_16x16x32_bf16 v[58:61], v[122:125], v[194:197], v[58:61]
	v_mfma_f32_16x16x32_bf16 v[102:105], v[114:117], v[202:205], v[102:105]
	v_mfma_f32_16x16x32_bf16 v[38:41], v[122:125], v[202:205], v[38:41]
	v_mfma_f32_16x16x32_bf16 v[94:97], v[114:117], v[210:213], v[94:97]
	v_mfma_f32_16x16x32_bf16 v[30:33], v[122:125], v[210:213], v[30:33]
	v_mfma_f32_16x16x32_bf16 v[158:161], v[118:121], v[190:193], v[158:161]
	v_mfma_f32_16x16x32_bf16 v[62:65], v[126:129], v[190:193], v[62:65]
	v_mfma_f32_16x16x32_bf16 v[154:157], v[118:121], v[198:201], v[154:157]
	v_mfma_f32_16x16x32_bf16 v[58:61], v[126:129], v[198:201], v[58:61]
	v_mfma_f32_16x16x32_bf16 v[102:105], v[118:121], v[206:209], v[102:105]
	v_mfma_f32_16x16x32_bf16 v[38:41], v[126:129], v[206:209], v[38:41]
	v_mfma_f32_16x16x32_bf16 v[94:97], v[118:121], v[214:217], v[94:97]
	v_mfma_f32_16x16x32_bf16 v[30:33], v[126:129], v[214:217], v[30:33]
	v_mfma_f32_16x16x32_bf16 v[150:153], v[130:133], v[142:145], v[150:153]
	v_mfma_f32_16x16x32_bf16 v[54:57], v[138:141], v[142:145], v[54:57]
	v_mfma_f32_16x16x32_bf16 v[142:145], v[130:133], v[194:197], v[146:149]
	v_mfma_f32_16x16x32_bf16 v[50:53], v[138:141], v[194:197], v[50:53]
	v_mfma_f32_16x16x32_bf16 v[98:101], v[130:133], v[202:205], v[98:101]
	v_mfma_f32_16x16x32_bf16 v[34:37], v[138:141], v[202:205], v[34:37]
	v_mfma_f32_16x16x32_bf16 v[90:93], v[130:133], v[210:213], v[90:93]
	v_mfma_f32_16x16x32_bf16 v[26:29], v[138:141], v[210:213], v[26:29]
	v_mfma_f32_16x16x32_bf16 v[150:153], v[134:137], v[190:193], v[150:153]
	v_mfma_f32_16x16x32_bf16 v[54:57], v[186:189], v[190:193], v[54:57]
	v_mfma_f32_16x16x32_bf16 v[146:149], v[134:137], v[198:201], v[142:145]
	v_mfma_f32_16x16x32_bf16 v[50:53], v[186:189], v[198:201], v[50:53]
	v_mfma_f32_16x16x32_bf16 v[98:101], v[134:137], v[206:209], v[98:101]
	v_mfma_f32_16x16x32_bf16 v[34:37], v[186:189], v[206:209], v[34:37]
	v_mfma_f32_16x16x32_bf16 v[90:93], v[134:137], v[214:217], v[90:93]
	v_mfma_f32_16x16x32_bf16 v[26:29], v[186:189], v[214:217], v[26:29]
	s_barrier
; #define PG8_STAGE(bufoff, gbase, voff) do { _Pragma("unroll") for (int _i = 0; _i < 2; ++_i) \
;         __builtin_amdgcn_global_load_lds((const unsigned*)((const char*)(gbase) + (voff)[_i]), (LAS unsigned*)(lds + (bufoff) + ldsw + _i * 8192), 16, 0, 0); } while (0)
; #define PG8_LDA(dst, b, h) do { _Pragma("unroll") for (int m = 0; m < 4; ++m) _Pragma("unroll") for (int k = 0; k < 2; ++k) dst[m][k] = *(const LAS bf16x8*)(lds + PG8_SA(b, h) + aoff + m * 2048 + k * 1024); } while (0)
; #define PG8_MMA(ai, bj, At, Bt) do { __builtin_amdgcn_s_setprio(1); _Pragma("unroll") for (int m = 0; m < 4; ++m) _Pragma("unroll") for (int n = 0; n < 2; ++n) _Pragma("unroll") for (int k = 0; k < 2; ++k) \
;         acc[ai][bj][m][n] = __builtin_amdgcn_mfma_f32_16x16x32_bf16(Bt[n][k], At[m][k], acc[ai][bj][m][n], 0, 0, 0); __builtin_amdgcn_s_setprio(0); } while (0)
; #define PG8_WAIT_V(n) asm volatile("s_waitcnt vmcnt(" #n ")" ::: "memory")
; #define PG8_WAIT_L(n) asm volatile("s_waitcnt lgkmcnt(" #n ")" ::: "memory")
; #define PG8_BAR __builtin_amdgcn_s_barrier()
; #define PG8_SCHED __builtin_amdgcn_sched_barrier(0)
; template <class Epi, bool UPMODE>
; __device__ __forceinline__ void gemm_phase(LAS unsigned char* lds, const Gemm g, const StaticOrder& S, const Epi& E) {
;     ...
;             PG8_LDA(At, 1, 1); PG8_STAGE(PG8_SB(1, 0), b3, voffB); PG8_STAGE(PG8_SB(1, 1), b3 + hstepB, voffB); PG8_STAGE(PG8_SA(1, 0), a3, voffA);
;             PG8_WAIT_V(8); PG8_WAIT_L(0); PG8_BAR; PG8_MMA(1, 0, At, B0); PG8_MMA(1, 1, At, B1); PG8_BAR; PG8_SCHED;
;         }
;         if (wr == 0) PG8_BAR;
	s_add_i32 s14, s25, s51
	v_lshl_add_u64 v[142:143], v[222:223], 0, s[74:75]
	s_mov_b32 m0, s14
	ds_read_b128 v[190:193], v254 offset:49152
	ds_read_b128 v[194:197], v254 offset:50176
	ds_read_b128 v[198:201], v254 offset:51200
	ds_read_b128 v[202:205], v254 offset:52224
	ds_read_b128 v[206:209], v254 offset:53248
	ds_read_b128 v[210:213], v254 offset:54272
	ds_read_b128 v[214:217], v254 offset:55296
	ds_read_b128 v[218:221], v254 offset:56320
	global_load_lds_dwordx4 v[142:143], off
	s_add_i32 m0, s14, 0x2000
	s_add_u32 s14, s16, 0x40080
	v_lshl_add_u64 v[142:143], v[224:225], 0, s[74:75]
	s_addc_u32 s15, s17, 0
	s_add_i32 s16, s28, s51
	global_load_lds_dwordx4 v[142:143], off
	v_lshl_add_u64 v[142:143], s[14:15], 0, v[162:163]
	s_mov_b32 m0, s16
	s_nop 0
	global_load_lds_dwordx4 v[142:143], off
	v_lshl_add_u64 v[142:143], s[14:15], 0, v[180:181]
	s_add_i32 m0, s16, 0x2000
	s_nop 0
	global_load_lds_dwordx4 v[142:143], off
	v_lshl_add_u64 v[142:143], v[226:227], 0, s[74:75]
	s_mov_b32 m0, s90
	s_nop 0
	global_load_lds_dwordx4 v[142:143], off
	v_lshl_add_u64 v[142:143], v[228:229], 0, s[74:75]
	s_mov_b32 m0, s91
	s_nop 0
	global_load_lds_dwordx4 v[142:143], off
	s_waitcnt vmcnt(8)
	s_waitcnt lgkmcnt(0)
	s_barrier
	s_waitcnt lgkmcnt(0)
	v_mfma_f32_16x16x32_bf16 v[86:89], v[114:117], v[190:193], v[86:89]
	v_mfma_f32_16x16x32_bf16 v[22:25], v[122:125], v[190:193], v[22:25]
	v_mfma_f32_16x16x32_bf16 v[78:81], v[114:117], v[198:201], v[78:81]
	v_mfma_f32_16x16x32_bf16 v[14:17], v[122:125], v[198:201], v[14:17]
	v_mfma_f32_16x16x32_bf16 v[70:73], v[114:117], v[206:209], v[70:73]
	v_mfma_f32_16x16x32_bf16 v[6:9], v[122:125], v[206:209], v[6:9]
	v_mfma_f32_16x16x32_bf16 v[106:109], v[114:117], v[214:217], v[106:109]
	v_mfma_f32_16x16x32_bf16 v[46:49], v[122:125], v[214:217], v[46:49]
	v_mfma_f32_16x16x32_bf16 v[86:89], v[118:121], v[194:197], v[86:89]
	v_mfma_f32_16x16x32_bf16 v[22:25], v[126:129], v[194:197], v[22:25]
	v_mfma_f32_16x16x32_bf16 v[78:81], v[118:121], v[202:205], v[78:81]
	v_mfma_f32_16x16x32_bf16 v[14:17], v[126:129], v[202:205], v[14:17]
	v_mfma_f32_16x16x32_bf16 v[70:73], v[118:121], v[210:213], v[70:73]
	v_mfma_f32_16x16x32_bf16 v[6:9], v[126:129], v[210:213], v[6:9]
	v_mfma_f32_16x16x32_bf16 v[142:145], v[118:121], v[218:221], v[106:109]
	v_mfma_f32_16x16x32_bf16 v[46:49], v[126:129], v[218:221], v[46:49]
	v_mfma_f32_16x16x32_bf16 v[82:85], v[130:133], v[190:193], v[82:85]
	v_mfma_f32_16x16x32_bf16 v[18:21], v[138:141], v[190:193], v[18:21]
	v_mfma_f32_16x16x32_bf16 v[74:77], v[130:133], v[198:201], v[74:77]
	v_mfma_f32_16x16x32_bf16 v[10:13], v[138:141], v[198:201], v[10:13]
	v_mfma_f32_16x16x32_bf16 v[66:69], v[130:133], v[206:209], v[66:69]
	v_mfma_f32_16x16x32_bf16 v[2:5], v[138:141], v[206:209], v[2:5]
	v_mfma_f32_16x16x32_bf16 v[106:109], v[130:133], v[214:217], v[110:113]
	v_mfma_f32_16x16x32_bf16 v[42:45], v[138:141], v[214:217], v[42:45]
	v_mfma_f32_16x16x32_bf16 v[82:85], v[134:137], v[194:197], v[82:85]
	v_mfma_f32_16x16x32_bf16 v[18:21], v[186:189], v[194:197], v[18:21]
	v_mfma_f32_16x16x32_bf16 v[74:77], v[134:137], v[202:205], v[74:77]
	v_mfma_f32_16x16x32_bf16 v[10:13], v[186:189], v[202:205], v[10:13]
	v_mfma_f32_16x16x32_bf16 v[66:69], v[134:137], v[210:213], v[66:69]
	v_mfma_f32_16x16x32_bf16 v[2:5], v[186:189], v[210:213], v[2:5]
	v_mfma_f32_16x16x32_bf16 v[134:137], v[134:137], v[218:221], v[106:109]
	v_mfma_f32_16x16x32_bf16 v[42:45], v[186:189], v[218:221], v[42:45]
	s_barrier
	s_add_i32 s24, s24, 2
	s_add_u32 s21, s21, 0x100
	s_addc_u32 s23, s23, 0
	s_cmp_gt_u32 s24, 13
	s_mov_b64 s[14:15], s[10:11]
	s_cbranch_scc0 .LBB0_595
	s_and_b64 vcc, exec, s[58:59]
	s_cbranch_vccz .LBB0_598
	s_barrier

; #define PG8_STAGE(bufoff, gbase, voff) do { _Pragma("unroll") for (int _i = 0; _i < 2; ++_i) \
;         __builtin_amdgcn_global_load_lds((const unsigned*)((const char*)(gbase) + (voff)[_i]), (LAS unsigned*)(lds + (bufoff) + ldsw + _i * 8192), 16, 0, 0); } while (0)
; #define PG8_LDA(dst, b, h) do { _Pragma("unroll") for (int m = 0; m < 4; ++m) _Pragma("unroll") for (int k = 0; k < 2; ++k) dst[m][k] = *(const LAS bf16x8*)(lds + PG8_SA(b, h) + aoff + m * 2048 + k * 1024); } while (0)
; #define PG8_LDB(dst, b, h) do { _Pragma("unroll") for (int n = 0; n < 2; ++n) _Pragma("unroll") for (int k = 0; k < 2; ++k) dst[n][k] = *(const LAS bf16x8*)(lds + PG8_SB(b, h) + boff + n * 2048 + k * 1024); } while (0)
; #define PG8_MMA(ai, bj, At, Bt) do { __builtin_amdgcn_s_setprio(1); _Pragma("unroll") for (int m = 0; m < 4; ++m) _Pragma("unroll") for (int n = 0; n < 2; ++n) _Pragma("unroll") for (int k = 0; k < 2; ++k) \
;         acc[ai][bj][m][n] = __builtin_amdgcn_mfma_f32_16x16x32_bf16(Bt[n][k], At[m][k], acc[ai][bj][m][n], 0, 0, 0); __builtin_amdgcn_s_setprio(0); } while (0)
; #define PG8_WAIT_V(n) asm volatile("s_waitcnt vmcnt(" #n ")" ::: "memory")
; #define PG8_WAIT_L(n) asm volatile("s_waitcnt lgkmcnt(" #n ")" ::: "memory")
; #define PG8_BAR __builtin_amdgcn_s_barrier()
; #define PG8_SCHED __builtin_amdgcn_sched_barrier(0)
; template <class Epi, bool UPMODE>
; __device__ __forceinline__ void gemm_phase(LAS unsigned char* lds, const Gemm g, const StaticOrder& S, const Epi& E) {
;     ...
;             const bool last = (t == nt - 2);
;             const char* a1 = cA + (size_t)(t + 1) * kstep;
;             const char* a2 = last ? nA : cA + (size_t)(t + 2) * kstep; const char* b2 = last ? nB : cB + (size_t)(t + 2) * kstep;
;             const char* a3 = a2 + kstep; const char* b3 = b2 + kstep;
;             PG8_LDB(B0, 0, 0); PG8_LDB(B1, 0, 1); PG8_SCHED; PG8_LDA(At, 0, 0); PG8_STAGE(PG8_SA(1, 1), a1 + hstepA, voffA);
;             PG8_WAIT_V(8); PG8_WAIT_L(0); PG8_BAR; PG8_MMA(0, 0, At, B0); PG8_MMA(0, 1, At, B1); PG8_BAR; PG8_SCHED;
;             PG8_LDA(At, 0, 1); PG8_STAGE(PG8_SB(0, 0), b2, voffB); PG8_STAGE(PG8_SB(0, 1), b2 + hstepB, voffB); PG8_STAGE(PG8_SA(0, 0), a2, voffA);
.LBB0_716:
	s_add_u32 s26, s24, 0x100
	s_addc_u32 s27, s25, 0
	s_add_i32 s58, 0, 0x10000
	s_cmp_eq_u32 s57, 40
	s_cselect_b32 s35, s9, s27
	s_cselect_b32 s34, s8, s26
	v_add_u32_e32 v144, s58, v147
	s_cselect_b32 s29, s23, s56
	s_cselect_b32 s28, s22, s55
	s_add_i32 s59, 0, 0x14000
	ds_read_b128 v[140:143], v144
	ds_read_b128 v[150:153], v144 offset:1024
	ds_read_b128 v[154:157], v144 offset:2048
	ds_read_b128 v[158:161], v144 offset:3072
	v_add_u32_e32 v144, s59, v147
	ds_read_b128 v[176:179], v144
	ds_read_b128 v[180:183], v144 offset:1024
	ds_read_b128 v[184:187], v144 offset:2048
	ds_read_b128 v[188:191], v144 offset:3072
	v_lshl_add_u64 v[144:145], s[24:25], 0, v[136:137]
	s_add_i32 m0, s40, 0xc000
	ds_read_b128 v[192:195], v149
	ds_read_b128 v[196:199], v149 offset:1024
	ds_read_b128 v[200:203], v149 offset:2048
	ds_read_b128 v[204:207], v149 offset:3072
	ds_read_b128 v[208:211], v149 offset:4096
	ds_read_b128 v[212:215], v149 offset:5120
	ds_read_b128 v[216:219], v149 offset:6144
	ds_read_b128 v[220:223], v149 offset:7168
	global_load_lds_dwordx4 v[144:145], off
	v_lshl_add_u64 v[144:145], s[24:25], 0, v[138:139]
	s_add_i32 m0, s40, 0xe000
	s_nop 0
	global_load_lds_dwordx4 v[144:145], off
	s_waitcnt vmcnt(8)
	s_waitcnt lgkmcnt(0)
	s_barrier
	s_waitcnt lgkmcnt(0)
	v_mfma_f32_16x16x32_bf16 v[126:129], v[140:143], v[192:195], v[126:129]
	v_mfma_f32_16x16x32_bf16 v[122:125], v[154:157], v[192:195], v[122:125]
	v_mfma_f32_16x16x32_bf16 v[110:113], v[140:143], v[200:203], v[110:113]
	v_mfma_f32_16x16x32_bf16 v[106:109], v[154:157], v[200:203], v[106:109]
	v_mfma_f32_16x16x32_bf16 v[94:97], v[140:143], v[208:211], v[94:97]
	v_mfma_f32_16x16x32_bf16 v[90:93], v[154:157], v[208:211], v[90:93]
	v_mfma_f32_16x16x32_bf16 v[78:81], v[140:143], v[216:219], v[78:81]
	v_mfma_f32_16x16x32_bf16 v[74:77], v[154:157], v[216:219], v[74:77]
	v_mfma_f32_16x16x32_bf16 v[126:129], v[150:153], v[196:199], v[126:129]
	v_mfma_f32_16x16x32_bf16 v[122:125], v[158:161], v[196:199], v[122:125]
	v_mfma_f32_16x16x32_bf16 v[110:113], v[150:153], v[204:207], v[110:113]
	v_mfma_f32_16x16x32_bf16 v[106:109], v[158:161], v[204:207], v[106:109]
	v_mfma_f32_16x16x32_bf16 v[94:97], v[150:153], v[212:215], v[94:97]
	v_mfma_f32_16x16x32_bf16 v[90:93], v[158:161], v[212:215], v[90:93]
	v_mfma_f32_16x16x32_bf16 v[78:81], v[150:153], v[220:223], v[78:81]
	v_mfma_f32_16x16x32_bf16 v[74:77], v[158:161], v[220:223], v[74:77]
	v_mfma_f32_16x16x32_bf16 v[118:121], v[176:179], v[192:195], v[118:121]
	v_mfma_f32_16x16x32_bf16 v[114:117], v[184:187], v[192:195], v[114:117]
	v_mfma_f32_16x16x32_bf16 v[102:105], v[176:179], v[200:203], v[102:105]
	v_mfma_f32_16x16x32_bf16 v[98:101], v[184:187], v[200:203], v[98:101]
	v_mfma_f32_16x16x32_bf16 v[86:89], v[176:179], v[208:211], v[86:89]
	v_mfma_f32_16x16x32_bf16 v[82:85], v[184:187], v[208:211], v[82:85]
	v_mfma_f32_16x16x32_bf16 v[70:73], v[176:179], v[216:219], v[70:73]
	v_mfma_f32_16x16x32_bf16 v[66:69], v[184:187], v[216:219], v[66:69]
	v_mfma_f32_16x16x32_bf16 v[118:121], v[180:183], v[196:199], v[118:121]
	v_mfma_f32_16x16x32_bf16 v[114:117], v[188:191], v[196:199], v[114:117]
	v_mfma_f32_16x16x32_bf16 v[102:105], v[180:183], v[204:207], v[102:105]
	v_mfma_f32_16x16x32_bf16 v[98:101], v[188:191], v[204:207], v[98:101]
	v_mfma_f32_16x16x32_bf16 v[86:89], v[180:183], v[212:215], v[86:89]
	v_mfma_f32_16x16x32_bf16 v[82:85], v[188:191], v[212:215], v[82:85]
	v_mfma_f32_16x16x32_bf16 v[70:73], v[180:183], v[220:223], v[70:73]
	v_mfma_f32_16x16x32_bf16 v[66:69], v[188:191], v[220:223], v[66:69]
	s_barrier
	s_add_i32 s24, s58, s31
	v_lshl_add_u64 v[144:145], s[28:29], 0, v[162:163]
	s_mov_b32 m0, s24
	ds_read_b128 v[192:195], v149 offset:16384
	ds_read_b128 v[196:199], v149 offset:17408
	ds_read_b128 v[200:203], v149 offset:18432
	ds_read_b128 v[204:207], v149 offset:19456
	ds_read_b128 v[208:211], v149 offset:20480
	ds_read_b128 v[212:215], v149 offset:21504
	ds_read_b128 v[216:219], v149 offset:22528
	ds_read_b128 v[220:223], v149 offset:23552
	global_load_lds_dwordx4 v[144:145], off
	s_add_i32 m0, s24, 0x2000
	s_add_u32 s24, s28, 0xb0000
	v_lshl_add_u64 v[224:225], s[28:29], 0, v[130:131]
	s_addc_u32 s25, s29, 0
	s_add_i32 s58, s59, s31
	global_load_lds_dwordx4 v[224:225], off
	v_lshl_add_u64 v[226:227], s[24:25], 0, v[162:163]
	s_mov_b32 m0, s58
	v_lshl_add_u64 v[228:229], s[34:35], 0, v[132:133]
	global_load_lds_dwordx4 v[226:227], off
	v_lshl_add_u64 v[226:227], s[24:25], 0, v[130:131]
	s_add_i32 m0, s58, 0x2000
	s_nop 0
	global_load_lds_dwordx4 v[226:227], off
	v_lshl_add_u64 v[226:227], s[34:35], 0, v[134:135]
	s_mov_b32 m0, s40
	s_nop 0
	global_load_lds_dwordx4 v[226:227], off
	s_mov_b32 m0, s42
	s_nop 0
	global_load_lds_dwordx4 v[228:229], off
	s_waitcnt vmcnt(8)
	s_waitcnt lgkmcnt(0)
	s_barrier
; #define PG8_STAGE(bufoff, gbase, voff) do { _Pragma("unroll") for (int _i = 0; _i < 2; ++_i) \
;         __builtin_amdgcn_global_load_lds((const unsigned*)((const char*)(gbase) + (voff)[_i]), (LAS unsigned*)(lds + (bufoff) + ldsw + _i * 8192), 16, 0, 0); } while (0)
; #define PG8_LDA(dst, b, h) do { _Pragma("unroll") for (int m = 0; m < 4; ++m) _Pragma("unroll") for (int k = 0; k < 2; ++k) dst[m][k] = *(const LAS bf16x8*)(lds + PG8_SA(b, h) + aoff + m * 2048 + k * 1024); } while (0)
; #define PG8_LDB(dst, b, h) do { _Pragma("unroll") for (int n = 0; n < 2; ++n) _Pragma("unroll") for (int k = 0; k < 2; ++k) dst[n][k] = *(const LAS bf16x8*)(lds + PG8_SB(b, h) + boff + n * 2048 + k * 1024); } while (0)
; #define PG8_MMA(ai, bj, At, Bt) do { __builtin_amdgcn_s_setprio(1); _Pragma("unroll") for (int m = 0; m < 4; ++m) _Pragma("unroll") for (int n = 0; n < 2; ++n) _Pragma("unroll") for (int k = 0; k < 2; ++k) \
;         acc[ai][bj][m][n] = __builtin_amdgcn_mfma_f32_16x16x32_bf16(Bt[n][k], At[m][k], acc[ai][bj][m][n], 0, 0, 0); __builtin_amdgcn_s_setprio(0); } while (0)
; #define PG8_WAIT_V(n) asm volatile("s_waitcnt vmcnt(" #n ")" ::: "memory")
; #define PG8_WAIT_L(n) asm volatile("s_waitcnt lgkmcnt(" #n ")" ::: "memory")
; #define PG8_BAR __builtin_amdgcn_s_barrier()
; #define PG8_SCHED __builtin_amdgcn_sched_barrier(0)
; template <class Epi, bool UPMODE>
; __device__ __forceinline__ void gemm_phase(LAS unsigned char* lds, const Gemm g, const StaticOrder& S, const Epi& E) {
;     ...
;             PG8_WAIT_V(8); PG8_WAIT_L(0); PG8_BAR; PG8_MMA(1, 0, At, B0); PG8_MMA(1, 1, At, B1); PG8_BAR; PG8_SCHED;
;             PG8_LDB(B0, 1, 0); PG8_LDB(B1, 1, 1); PG8_SCHED; PG8_LDA(At, 1, 0); PG8_STAGE(PG8_SA(0, 1), a2 + hstepA, voffA);
;             PG8_WAIT_V(8); PG8_WAIT_L(0); PG8_BAR; PG8_MMA(0, 0, At, B0); PG8_MMA(0, 1, At, B1); PG8_BAR; PG8_SCHED;
	s_waitcnt lgkmcnt(0)
	v_mfma_f32_16x16x32_bf16 v[62:65], v[140:143], v[192:195], v[62:65]
	v_mfma_f32_16x16x32_bf16 v[58:61], v[154:157], v[192:195], v[58:61]
	v_mfma_f32_16x16x32_bf16 v[46:49], v[140:143], v[200:203], v[46:49]
	v_mfma_f32_16x16x32_bf16 v[42:45], v[154:157], v[200:203], v[42:45]
	v_mfma_f32_16x16x32_bf16 v[30:33], v[140:143], v[208:211], v[30:33]
	v_mfma_f32_16x16x32_bf16 v[26:29], v[154:157], v[208:211], v[26:29]
	v_mfma_f32_16x16x32_bf16 v[14:17], v[140:143], v[216:219], v[14:17]
	v_mfma_f32_16x16x32_bf16 v[10:13], v[154:157], v[216:219], v[10:13]
	v_mfma_f32_16x16x32_bf16 v[62:65], v[150:153], v[196:199], v[62:65]
	v_mfma_f32_16x16x32_bf16 v[58:61], v[158:161], v[196:199], v[58:61]
	v_mfma_f32_16x16x32_bf16 v[46:49], v[150:153], v[204:207], v[46:49]
	v_mfma_f32_16x16x32_bf16 v[42:45], v[158:161], v[204:207], v[42:45]
	v_mfma_f32_16x16x32_bf16 v[30:33], v[150:153], v[212:215], v[30:33]
	v_mfma_f32_16x16x32_bf16 v[26:29], v[158:161], v[212:215], v[26:29]
	v_mfma_f32_16x16x32_bf16 v[14:17], v[150:153], v[220:223], v[14:17]
	v_mfma_f32_16x16x32_bf16 v[10:13], v[158:161], v[220:223], v[10:13]
	v_mfma_f32_16x16x32_bf16 v[54:57], v[176:179], v[192:195], v[54:57]
	v_mfma_f32_16x16x32_bf16 v[50:53], v[184:187], v[192:195], v[50:53]
	v_mfma_f32_16x16x32_bf16 v[38:41], v[176:179], v[200:203], v[38:41]
	v_mfma_f32_16x16x32_bf16 v[34:37], v[184:187], v[200:203], v[34:37]
	v_mfma_f32_16x16x32_bf16 v[22:25], v[176:179], v[208:211], v[22:25]
	v_mfma_f32_16x16x32_bf16 v[18:21], v[184:187], v[208:211], v[18:21]
	v_mfma_f32_16x16x32_bf16 v[6:9], v[176:179], v[216:219], v[6:9]
	v_mfma_f32_16x16x32_bf16 v[2:5], v[184:187], v[216:219], v[2:5]
	v_mfma_f32_16x16x32_bf16 v[54:57], v[180:183], v[196:199], v[54:57]
	v_mfma_f32_16x16x32_bf16 v[50:53], v[188:191], v[196:199], v[50:53]
	v_mfma_f32_16x16x32_bf16 v[38:41], v[180:183], v[204:207], v[38:41]
	v_mfma_f32_16x16x32_bf16 v[34:37], v[188:191], v[204:207], v[34:37]
	v_mfma_f32_16x16x32_bf16 v[22:25], v[180:183], v[212:215], v[22:25]
	v_mfma_f32_16x16x32_bf16 v[18:21], v[188:191], v[212:215], v[18:21]
	v_mfma_f32_16x16x32_bf16 v[6:9], v[180:183], v[220:223], v[6:9]
	v_mfma_f32_16x16x32_bf16 v[2:5], v[188:191], v[220:223], v[2:5]
	s_barrier
	s_add_i32 s58, 0, 0x18000
	s_add_i32 s59, 0, 0x1c000
	v_add_u32_e32 v158, s58, v147
	v_add_u32_e32 v188, s59, v147
	ds_read_b128 v[140:143], v158
	ds_read_b128 v[150:153], v158 offset:1024
	ds_read_b128 v[154:157], v158 offset:2048
	ds_read_b128 v[158:161], v158 offset:3072
	ds_read_b128 v[176:179], v188
	ds_read_b128 v[180:183], v188 offset:1024
	ds_read_b128 v[184:187], v188 offset:2048
	ds_read_b128 v[188:191], v188 offset:3072
	s_add_u32 s24, s34, 0xb0000
	s_addc_u32 s25, s35, 0
	s_mov_b32 m0, s43
	v_lshl_add_u64 v[230:231], s[24:25], 0, v[134:135]
	ds_read_b128 v[192:195], v149 offset:32768
	ds_read_b128 v[196:199], v149 offset:33792
	ds_read_b128 v[200:203], v149 offset:34816
	ds_read_b128 v[204:207], v149 offset:35840
	ds_read_b128 v[208:211], v149 offset:36864
	ds_read_b128 v[212:215], v149 offset:37888
	ds_read_b128 v[216:219], v149 offset:38912
	ds_read_b128 v[220:223], v149 offset:39936
	global_load_lds_dwordx4 v[230:231], off
	v_lshl_add_u64 v[230:231], s[24:25], 0, v[132:133]
	s_mov_b32 m0, s44
	s_nop 0
	global_load_lds_dwordx4 v[230:231], off
	s_waitcnt vmcnt(8)
	s_waitcnt lgkmcnt(0)
	s_barrier
	s_waitcnt lgkmcnt(0)
	v_mfma_f32_16x16x32_bf16 v[126:129], v[140:143], v[192:195], v[126:129]
	v_mfma_f32_16x16x32_bf16 v[122:125], v[154:157], v[192:195], v[122:125]
	v_mfma_f32_16x16x32_bf16 v[110:113], v[140:143], v[200:203], v[110:113]
	v_mfma_f32_16x16x32_bf16 v[106:109], v[154:157], v[200:203], v[106:109]
	v_mfma_f32_16x16x32_bf16 v[94:97], v[140:143], v[208:211], v[94:97]
	v_mfma_f32_16x16x32_bf16 v[90:93], v[154:157], v[208:211], v[90:93]
	v_mfma_f32_16x16x32_bf16 v[78:81], v[140:143], v[216:219], v[78:81]
	v_mfma_f32_16x16x32_bf16 v[74:77], v[154:157], v[216:219], v[74:77]
	v_mfma_f32_16x16x32_bf16 v[126:129], v[150:153], v[196:199], v[126:129]
	v_mfma_f32_16x16x32_bf16 v[122:125], v[158:161], v[196:199], v[122:125]
	v_mfma_f32_16x16x32_bf16 v[110:113], v[150:153], v[204:207], v[110:113]
	v_mfma_f32_16x16x32_bf16 v[106:109], v[158:161], v[204:207], v[106:109]
	v_mfma_f32_16x16x32_bf16 v[94:97], v[150:153], v[212:215], v[94:97]
	v_mfma_f32_16x16x32_bf16 v[90:93], v[158:161], v[212:215], v[90:93]
	v_mfma_f32_16x16x32_bf16 v[78:81], v[150:153], v[220:223], v[78:81]
	v_mfma_f32_16x16x32_bf16 v[74:77], v[158:161], v[220:223], v[74:77]
	v_mfma_f32_16x16x32_bf16 v[118:121], v[176:179], v[192:195], v[118:121]
	v_mfma_f32_16x16x32_bf16 v[114:117], v[184:187], v[192:195], v[114:117]
	v_mfma_f32_16x16x32_bf16 v[102:105], v[176:179], v[200:203], v[102:105]
	v_mfma_f32_16x16x32_bf16 v[98:101], v[184:187], v[200:203], v[98:101]
	v_mfma_f32_16x16x32_bf16 v[86:89], v[176:179], v[208:211], v[86:89]
	v_mfma_f32_16x16x32_bf16 v[82:85], v[184:187], v[208:211], v[82:85]
	v_mfma_f32_16x16x32_bf16 v[70:73], v[176:179], v[216:219], v[70:73]
	v_mfma_f32_16x16x32_bf16 v[66:69], v[184:187], v[216:219], v[66:69]
	v_mfma_f32_16x16x32_bf16 v[118:121], v[180:183], v[196:199], v[118:121]
	v_mfma_f32_16x16x32_bf16 v[114:117], v[188:191], v[196:199], v[114:117]
	v_mfma_f32_16x16x32_bf16 v[102:105], v[180:183], v[204:207], v[102:105]
	v_mfma_f32_16x16x32_bf16 v[98:101], v[188:191], v[204:207], v[98:101]
	v_mfma_f32_16x16x32_bf16 v[86:89], v[180:183], v[212:215], v[86:89]
	v_mfma_f32_16x16x32_bf16 v[82:85], v[188:191], v[212:215], v[82:85]
	v_mfma_f32_16x16x32_bf16 v[70:73], v[180:183], v[220:223], v[70:73]
	v_mfma_f32_16x16x32_bf16 v[66:69], v[188:191], v[220:223], v[66:69]
	s_barrier
; #define PG8_STAGE(bufoff, gbase, voff) do { _Pragma("unroll") for (int _i = 0; _i < 2; ++_i) \
;         __builtin_amdgcn_global_load_lds((const unsigned*)((const char*)(gbase) + (voff)[_i]), (LAS unsigned*)(lds + (bufoff) + ldsw + _i * 8192), 16, 0, 0); } while (0)
; #define PG8_LDA(dst, b, h) do { _Pragma("unroll") for (int m = 0; m < 4; ++m) _Pragma("unroll") for (int k = 0; k < 2; ++k) dst[m][k] = *(const LAS bf16x8*)(lds + PG8_SA(b, h) + aoff + m * 2048 + k * 1024); } while (0)
; #define PG8_MMA(ai, bj, At, Bt) do { __builtin_amdgcn_s_setprio(1); _Pragma("unroll") for (int m = 0; m < 4; ++m) _Pragma("unroll") for (int n = 0; n < 2; ++n) _Pragma("unroll") for (int k = 0; k < 2; ++k) \
;         acc[ai][bj][m][n] = __builtin_amdgcn_mfma_f32_16x16x32_bf16(Bt[n][k], At[m][k], acc[ai][bj][m][n], 0, 0, 0); __builtin_amdgcn_s_setprio(0); } while (0)
; #define PG8_WAIT_V(n) asm volatile("s_waitcnt vmcnt(" #n ")" ::: "memory")
; #define PG8_WAIT_L(n) asm volatile("s_waitcnt lgkmcnt(" #n ")" ::: "memory")
; #define PG8_BAR __builtin_amdgcn_s_barrier()
; #define PG8_SCHED __builtin_amdgcn_sched_barrier(0)
; template <class Epi, bool UPMODE>
; __device__ __forceinline__ void gemm_phase(LAS unsigned char* lds, const Gemm g, const StaticOrder& S, const Epi& E) {
;     ...
;             PG8_LDA(At, 1, 1); PG8_STAGE(PG8_SB(1, 0), b3, voffB); PG8_STAGE(PG8_SB(1, 1), b3 + hstepB, voffB); PG8_STAGE(PG8_SA(1, 0), a3, voffA);
;             PG8_WAIT_V(8); PG8_WAIT_L(0); PG8_BAR; PG8_MMA(1, 0, At, B0); PG8_MMA(1, 1, At, B1); PG8_BAR; PG8_SCHED;
;         }
;         if (wr == 0) PG8_BAR;
	s_add_i32 s24, s58, s31
	v_lshl_add_u64 v[144:145], v[144:145], 0, s[74:75]
	s_mov_b32 m0, s24
	ds_read_b128 v[192:195], v149 offset:49152
	ds_read_b128 v[196:199], v149 offset:50176
	ds_read_b128 v[200:203], v149 offset:51200
	ds_read_b128 v[204:207], v149 offset:52224
	ds_read_b128 v[208:211], v149 offset:53248
	ds_read_b128 v[212:215], v149 offset:54272
	ds_read_b128 v[216:219], v149 offset:55296
	ds_read_b128 v[220:223], v149 offset:56320
	global_load_lds_dwordx4 v[144:145], off
	s_add_i32 m0, s24, 0x2000
	s_add_u32 s24, s28, 0xb0080
	v_lshl_add_u64 v[144:145], v[224:225], 0, s[74:75]
	s_addc_u32 s25, s29, 0
	s_add_i32 s28, s59, s31
	global_load_lds_dwordx4 v[144:145], off
	v_lshl_add_u64 v[144:145], s[24:25], 0, v[162:163]
	s_mov_b32 m0, s28
	s_nop 0
	global_load_lds_dwordx4 v[144:145], off
	v_lshl_add_u64 v[144:145], s[24:25], 0, v[130:131]
	s_add_i32 m0, s28, 0x2000
	s_nop 0
	global_load_lds_dwordx4 v[144:145], off
	v_lshl_add_u64 v[144:145], v[226:227], 0, s[74:75]
	s_mov_b32 m0, s46
	s_nop 0
	global_load_lds_dwordx4 v[144:145], off
	v_lshl_add_u64 v[144:145], v[228:229], 0, s[74:75]
	s_mov_b32 m0, s48
	s_nop 0
	global_load_lds_dwordx4 v[144:145], off
	s_waitcnt vmcnt(8)
	s_waitcnt lgkmcnt(0)
	s_barrier
	s_waitcnt lgkmcnt(0)
	v_mfma_f32_16x16x32_bf16 v[62:65], v[140:143], v[192:195], v[62:65]
	v_mfma_f32_16x16x32_bf16 v[58:61], v[154:157], v[192:195], v[58:61]
	v_mfma_f32_16x16x32_bf16 v[46:49], v[140:143], v[200:203], v[46:49]
	v_mfma_f32_16x16x32_bf16 v[42:45], v[154:157], v[200:203], v[42:45]
	v_mfma_f32_16x16x32_bf16 v[30:33], v[140:143], v[208:211], v[30:33]
	v_mfma_f32_16x16x32_bf16 v[26:29], v[154:157], v[208:211], v[26:29]
	v_mfma_f32_16x16x32_bf16 v[14:17], v[140:143], v[216:219], v[14:17]
	v_mfma_f32_16x16x32_bf16 v[10:13], v[154:157], v[216:219], v[10:13]
	v_mfma_f32_16x16x32_bf16 v[62:65], v[150:153], v[196:199], v[62:65]
	v_mfma_f32_16x16x32_bf16 v[58:61], v[158:161], v[196:199], v[58:61]
	v_mfma_f32_16x16x32_bf16 v[46:49], v[150:153], v[204:207], v[46:49]
	v_mfma_f32_16x16x32_bf16 v[42:45], v[158:161], v[204:207], v[42:45]
	v_mfma_f32_16x16x32_bf16 v[30:33], v[150:153], v[212:215], v[30:33]
	v_mfma_f32_16x16x32_bf16 v[26:29], v[158:161], v[212:215], v[26:29]
	v_mfma_f32_16x16x32_bf16 v[14:17], v[150:153], v[220:223], v[14:17]
	v_mfma_f32_16x16x32_bf16 v[10:13], v[158:161], v[220:223], v[10:13]
	v_mfma_f32_16x16x32_bf16 v[54:57], v[176:179], v[192:195], v[54:57]
	v_mfma_f32_16x16x32_bf16 v[50:53], v[184:187], v[192:195], v[50:53]
	v_mfma_f32_16x16x32_bf16 v[38:41], v[176:179], v[200:203], v[38:41]
	v_mfma_f32_16x16x32_bf16 v[34:37], v[184:187], v[200:203], v[34:37]
	v_mfma_f32_16x16x32_bf16 v[22:25], v[176:179], v[208:211], v[22:25]
	v_mfma_f32_16x16x32_bf16 v[18:21], v[184:187], v[208:211], v[18:21]
	v_mfma_f32_16x16x32_bf16 v[6:9], v[176:179], v[216:219], v[6:9]
	v_mfma_f32_16x16x32_bf16 v[2:5], v[184:187], v[216:219], v[2:5]
	v_mfma_f32_16x16x32_bf16 v[54:57], v[180:183], v[196:199], v[54:57]
	v_mfma_f32_16x16x32_bf16 v[50:53], v[188:191], v[196:199], v[50:53]
	v_mfma_f32_16x16x32_bf16 v[38:41], v[180:183], v[204:207], v[38:41]
	v_mfma_f32_16x16x32_bf16 v[34:37], v[188:191], v[204:207], v[34:37]
	v_mfma_f32_16x16x32_bf16 v[22:25], v[180:183], v[212:215], v[22:25]
	v_mfma_f32_16x16x32_bf16 v[18:21], v[188:191], v[212:215], v[18:21]
	v_mfma_f32_16x16x32_bf16 v[6:9], v[180:183], v[220:223], v[6:9]
	v_mfma_f32_16x16x32_bf16 v[2:5], v[188:191], v[220:223], v[2:5]
	s_barrier
	s_add_i32 s57, s57, 2
	s_add_u32 s55, s55, 0x100
	s_addc_u32 s56, s56, 0
	s_cmp_gt_u32 s57, 41
	s_mov_b64 s[24:25], s[26:27]
	s_cbranch_scc0 .LBB0_716
	s_and_b64 vcc, exec, s[20:21]
	s_cbranch_vccz .LBB0_719
	s_barrier
